# loop-edge edit (guide 7.11): in all five GEMM K-loops the counter updates, exit test and loop-back branch sit in front of the closing workgroup barrier, the barrier is the loop head, exit path has its
# baseline (speedup 1.0000x reference)
;     __device__ __forceinline__ long a_off(int pm, size_t tstep) const { return (long)pm * (long)tstep; }
; template <class Epi, class Sched, bool ALIGN_EPI = false, bool SP2 = false>
; __device__ __forceinline__ void gemm_phase(PG8_LAS unsigned char* lds, const Gemm g, const Sched& S, const Epi& E) {
;     ...
;     for (;;) {
;         const bool has_next = S.next(ui + 1, nxt);
;         const char* nA = has_next ? (const char*)g.A + S.a_off(nxt.pm, tstep) : cA; const char* nB = has_next ? (const char*)g.Bt + (size_t)nxt.pn * tstep : cB;
;         for (int t = 0; t < nt; t += 2) {
;             const bool last = (t == nt - 2);
.LBB0_274:
	s_lshr_b32 s32, s21, 1
	s_cmp_eq_u32 s32, 2
	s_cbranch_scc1 .Lp2_vloop
	s_branch .Lkbody0

; #define PG8_STAGE(bufoff, gbase, voff) do { _Pragma("unroll") for (int _i = 0; _i < 2; ++_i) \
;         __builtin_amdgcn_global_load_lds((const unsigned*)((const char*)(gbase) + (voff)[_i]), (PG8_LAS unsigned*)(lds + (bufoff) + ldsw + _i * 8192), 16, 0, 0); } while (0)
; #define PG8_LDA(dst, b, h) do { _Pragma("unroll") for (int m = 0; m < 4; ++m) _Pragma("unroll") for (int k = 0; k < 2; ++k) dst[m][k] = *(const PG8_LAS bf16x8*)(lds + PG8_SA(b, h) + aoff + m * 2048 + k * 1024); } while (0)
; #define PG8_LDB(dst, b, h) do { _Pragma("unroll") for (int n = 0; n < 2; ++n) _Pragma("unroll") for (int k = 0; k < 2; ++k) dst[n][k] = *(const PG8_LAS bf16x8*)(lds + PG8_SB(b, h) + boff + n * 2048 + k * 1024); } while (0)
; #define PG8_MMA(ai, bj, At, Bt) do { __builtin_amdgcn_s_setprio(1); _Pragma("unroll") for (int m = 0; m < 4; ++m) _Pragma("unroll") for (int n = 0; n < 2; ++n) _Pragma("unroll") for (int k = 0; k < 2; ++k) \
;         acc[ai][bj][m][n] = __builtin_amdgcn_mfma_f32_16x16x32_bf16(Bt[n][k], At[m][k], acc[ai][bj][m][n], 0, 0, 0); __builtin_amdgcn_s_setprio(0); } while (0)
; #define PG8_WAIT_V(n) asm volatile("s_waitcnt vmcnt(" #n ")" ::: "memory")
; #define PG8_WAIT_L(n) asm volatile("s_waitcnt lgkmcnt(" #n ")" ::: "memory")
; #define PG8_BAR __builtin_amdgcn_s_barrier()
; #define PG8_SCHED __builtin_amdgcn_sched_barrier(0)
; template <class Epi, class Sched, bool ALIGN_EPI = false, bool SP2 = false>
; __device__ __forceinline__ void gemm_phase(PG8_LAS unsigned char* lds, const Gemm g, const Sched& S, const Epi& E) {
;     ...
;             PG8_LDB(B0, 0, 0); PG8_LDB(B1, 0, 1); PG8_SCHED; PG8_LDA(At, 0, 0); PG8_STAGE(PG8_SA(1, 1), a1 + hstep, voffA);
;             PG8_WAIT_V(8); PG8_WAIT_L(0); PG8_BAR; PG8_MMA(0, 0, At, B0); PG8_MMA(0, 1, At, B1); PG8_BAR; PG8_SCHED;
;             PG8_LDA(At, 0, 1); PG8_STAGE(PG8_SB(0, 0), b2, voffB); PG8_STAGE(PG8_SB(0, 1), b2 + hstep, voffB); PG8_STAGE(PG8_SA(0, 0), a2, voffA);
;             PG8_WAIT_V(8); PG8_WAIT_L(0); PG8_BAR; PG8_MMA(1, 0, At, B0); PG8_MMA(1, 1, At, B1); PG8_BAR; PG8_SCHED;
.Lkbody0:
	ds_read_b128 v[146:149], v169
	ds_read_b128 v[150:153], v169 offset:1024
	ds_read_b128 v[178:181], v169 offset:2048
	ds_read_b128 v[182:185], v169 offset:3072
	ds_read_b128 v[186:189], v170
	ds_read_b128 v[190:193], v170 offset:1024
	ds_read_b128 v[194:197], v170 offset:2048
	ds_read_b128 v[198:201], v170 offset:3072
	s_add_u32 s0, s14, 0xfffc0080
	s_addc_u32 s1, s15, -1
	s_cmp_eq_u32 s93, 12
	s_cselect_b32 s53, s45, s1
	s_cselect_b32 s52, s89, s0
	s_cselect_b32 s51, s43, s92
	s_cselect_b32 s50, s90, s91
	v_lshl_add_u64 v[206:207], s[14:15], 0, v[138:139]
	s_add_i32 m0, s56, 0xc000
	ds_read_b128 v[202:205], v171
	ds_read_b128 v[210:213], v171 offset:1024
	ds_read_b128 v[214:217], v171 offset:2048
	ds_read_b128 v[218:221], v171 offset:3072
	ds_read_b128 v[222:225], v171 offset:4096
	ds_read_b128 v[226:229], v171 offset:5120
	ds_read_b128 v[230:233], v171 offset:6144
	ds_read_b128 v[234:237], v171 offset:7168
	global_load_lds_dwordx4 v[206:207], off
	v_lshl_add_u64 v[206:207], s[14:15], 0, v[140:141]
	s_add_i32 m0, s56, 0xe000
	s_nop 0
	global_load_lds_dwordx4 v[206:207], off
	s_waitcnt vmcnt(8)
	s_waitcnt lgkmcnt(0)
	s_barrier
	s_setprio 1
	s_waitcnt lgkmcnt(0)
	v_mfma_f32_16x16x32_bf16 v[124:127], v[146:149], v[202:205], v[124:127]
	v_mfma_f32_16x16x32_bf16 v[120:123], v[178:181], v[202:205], v[120:123]
	v_mfma_f32_16x16x32_bf16 v[112:115], v[146:149], v[214:217], v[112:115]
	v_mfma_f32_16x16x32_bf16 v[104:107], v[178:181], v[214:217], v[104:107]
	v_mfma_f32_16x16x32_bf16 v[96:99], v[146:149], v[222:225], v[96:99]
	v_mfma_f32_16x16x32_bf16 v[88:91], v[178:181], v[222:225], v[88:91]
	v_mfma_f32_16x16x32_bf16 v[80:83], v[146:149], v[230:233], v[80:83]
	v_mfma_f32_16x16x32_bf16 v[72:75], v[178:181], v[230:233], v[72:75]
	v_mfma_f32_16x16x32_bf16 v[124:127], v[150:153], v[210:213], v[124:127]
	v_mfma_f32_16x16x32_bf16 v[120:123], v[182:185], v[210:213], v[120:123]
	v_mfma_f32_16x16x32_bf16 v[112:115], v[150:153], v[218:221], v[112:115]
	v_mfma_f32_16x16x32_bf16 v[104:107], v[182:185], v[218:221], v[104:107]
	v_mfma_f32_16x16x32_bf16 v[96:99], v[150:153], v[226:229], v[96:99]
	v_mfma_f32_16x16x32_bf16 v[88:91], v[182:185], v[226:229], v[88:91]
	v_mfma_f32_16x16x32_bf16 v[80:83], v[150:153], v[234:237], v[80:83]
	v_mfma_f32_16x16x32_bf16 v[72:75], v[182:185], v[234:237], v[72:75]
	s_setprio 0
	s_setprio 1
	v_mfma_f32_16x16x32_bf16 v[116:119], v[186:189], v[202:205], v[116:119]
	v_mfma_f32_16x16x32_bf16 v[108:111], v[194:197], v[202:205], v[108:111]
	v_mfma_f32_16x16x32_bf16 v[100:103], v[186:189], v[214:217], v[100:103]
	v_mfma_f32_16x16x32_bf16 v[92:95], v[194:197], v[214:217], v[92:95]
	v_mfma_f32_16x16x32_bf16 v[84:87], v[186:189], v[222:225], v[84:87]
	v_mfma_f32_16x16x32_bf16 v[76:79], v[194:197], v[222:225], v[76:79]
	v_mfma_f32_16x16x32_bf16 v[68:71], v[186:189], v[230:233], v[68:71]
	v_mfma_f32_16x16x32_bf16 v[64:67], v[194:197], v[230:233], v[64:67]
	v_mfma_f32_16x16x32_bf16 v[116:119], v[190:193], v[210:213], v[116:119]
	v_mfma_f32_16x16x32_bf16 v[108:111], v[198:201], v[210:213], v[108:111]
	v_mfma_f32_16x16x32_bf16 v[100:103], v[190:193], v[218:221], v[100:103]
	v_mfma_f32_16x16x32_bf16 v[92:95], v[198:201], v[218:221], v[92:95]
	v_mfma_f32_16x16x32_bf16 v[84:87], v[190:193], v[226:229], v[84:87]
	v_mfma_f32_16x16x32_bf16 v[76:79], v[198:201], v[226:229], v[76:79]
	v_mfma_f32_16x16x32_bf16 v[68:71], v[190:193], v[234:237], v[68:71]
	v_mfma_f32_16x16x32_bf16 v[64:67], v[198:201], v[234:237], v[64:67]
	s_setprio 0
	s_barrier
	s_add_i32 s0, s74, s29
	v_lshl_add_u64 v[206:207], s[50:51], 0, v[132:133]
	s_mov_b32 m0, s0
	ds_read_b128 v[202:205], v171 offset:16384
	ds_read_b128 v[210:213], v171 offset:17408
	ds_read_b128 v[214:217], v171 offset:18432
	ds_read_b128 v[218:221], v171 offset:19456
	ds_read_b128 v[222:225], v171 offset:20480
	ds_read_b128 v[226:229], v171 offset:21504
	ds_read_b128 v[230:233], v171 offset:22528
	ds_read_b128 v[234:237], v171 offset:23552
	global_load_lds_dwordx4 v[206:207], off
	s_add_i32 m0, s0, 0x2000
	s_add_u32 s94, s50, 0x40000
	v_lshl_add_u64 v[238:239], s[50:51], 0, v[128:129]
	s_addc_u32 s95, s51, 0
	s_add_i32 s0, s75, s29
	global_load_lds_dwordx4 v[238:239], off
	v_lshl_add_u64 v[240:241], s[94:95], 0, v[132:133]
	s_mov_b32 m0, s0
	v_lshl_add_u64 v[242:243], s[52:53], 0, v[130:131]
	global_load_lds_dwordx4 v[240:241], off
	v_lshl_add_u64 v[240:241], s[94:95], 0, v[128:129]
	s_add_i32 m0, s0, 0x2000
	s_nop 0
	global_load_lds_dwordx4 v[240:241], off
	v_lshl_add_u64 v[240:241], s[52:53], 0, v[134:135]
	s_mov_b32 m0, s56
	s_nop 0
	global_load_lds_dwordx4 v[240:241], off
	s_mov_b32 m0, s57
	s_nop 0
	global_load_lds_dwordx4 v[242:243], off
	s_waitcnt vmcnt(8)
	s_waitcnt lgkmcnt(0)
	s_barrier
; #define PG8_STAGE(bufoff, gbase, voff) do { _Pragma("unroll") for (int _i = 0; _i < 2; ++_i) \
;         __builtin_amdgcn_global_load_lds((const unsigned*)((const char*)(gbase) + (voff)[_i]), (PG8_LAS unsigned*)(lds + (bufoff) + ldsw + _i * 8192), 16, 0, 0); } while (0)
; #define PG8_LDA(dst, b, h) do { _Pragma("unroll") for (int m = 0; m < 4; ++m) _Pragma("unroll") for (int k = 0; k < 2; ++k) dst[m][k] = *(const PG8_LAS bf16x8*)(lds + PG8_SA(b, h) + aoff + m * 2048 + k * 1024); } while (0)
; #define PG8_LDB(dst, b, h) do { _Pragma("unroll") for (int n = 0; n < 2; ++n) _Pragma("unroll") for (int k = 0; k < 2; ++k) dst[n][k] = *(const PG8_LAS bf16x8*)(lds + PG8_SB(b, h) + boff + n * 2048 + k * 1024); } while (0)
; #define PG8_MMA(ai, bj, At, Bt) do { __builtin_amdgcn_s_setprio(1); _Pragma("unroll") for (int m = 0; m < 4; ++m) _Pragma("unroll") for (int n = 0; n < 2; ++n) _Pragma("unroll") for (int k = 0; k < 2; ++k) \
;         acc[ai][bj][m][n] = __builtin_amdgcn_mfma_f32_16x16x32_bf16(Bt[n][k], At[m][k], acc[ai][bj][m][n], 0, 0, 0); __builtin_amdgcn_s_setprio(0); } while (0)
; #define PG8_WAIT_V(n) asm volatile("s_waitcnt vmcnt(" #n ")" ::: "memory")
; #define PG8_WAIT_L(n) asm volatile("s_waitcnt lgkmcnt(" #n ")" ::: "memory")
; #define PG8_BAR __builtin_amdgcn_s_barrier()
; #define PG8_SCHED __builtin_amdgcn_sched_barrier(0)
; template <class Epi, class Sched, bool ALIGN_EPI = false, bool SP2 = false>
; __device__ __forceinline__ void gemm_phase(PG8_LAS unsigned char* lds, const Gemm g, const Sched& S, const Epi& E) {
;     ...
;             PG8_WAIT_V(8); PG8_WAIT_L(0); PG8_BAR; PG8_MMA(1, 0, At, B0); PG8_MMA(1, 1, At, B1); PG8_BAR; PG8_SCHED;
;             PG8_LDB(B0, 1, 0); PG8_LDB(B1, 1, 1); PG8_SCHED; PG8_LDA(At, 1, 0); PG8_STAGE(PG8_SA(0, 1), a2 + hstep, voffA);
;             PG8_WAIT_V(8); PG8_WAIT_L(0); PG8_BAR; PG8_MMA(0, 0, At, B0); PG8_MMA(0, 1, At, B1); PG8_BAR; PG8_SCHED;
	s_setprio 1
	s_waitcnt lgkmcnt(0)
	v_mfma_f32_16x16x32_bf16 v[60:63], v[146:149], v[202:205], v[60:63]
	v_mfma_f32_16x16x32_bf16 v[56:59], v[178:181], v[202:205], v[56:59]
	v_mfma_f32_16x16x32_bf16 v[48:51], v[146:149], v[214:217], v[48:51]
	v_mfma_f32_16x16x32_bf16 v[40:43], v[178:181], v[214:217], v[40:43]
	v_mfma_f32_16x16x32_bf16 v[32:35], v[146:149], v[222:225], v[32:35]
	v_mfma_f32_16x16x32_bf16 v[24:27], v[178:181], v[222:225], v[24:27]
	v_mfma_f32_16x16x32_bf16 v[16:19], v[146:149], v[230:233], v[16:19]
	v_mfma_f32_16x16x32_bf16 v[8:11], v[178:181], v[230:233], v[8:11]
	v_mfma_f32_16x16x32_bf16 v[60:63], v[150:153], v[210:213], v[60:63]
	v_mfma_f32_16x16x32_bf16 v[56:59], v[182:185], v[210:213], v[56:59]
	v_mfma_f32_16x16x32_bf16 v[48:51], v[150:153], v[218:221], v[48:51]
	v_mfma_f32_16x16x32_bf16 v[40:43], v[182:185], v[218:221], v[40:43]
	v_mfma_f32_16x16x32_bf16 v[32:35], v[150:153], v[226:229], v[32:35]
	v_mfma_f32_16x16x32_bf16 v[24:27], v[182:185], v[226:229], v[24:27]
	v_mfma_f32_16x16x32_bf16 v[16:19], v[150:153], v[234:237], v[16:19]
	v_mfma_f32_16x16x32_bf16 v[8:11], v[182:185], v[234:237], v[8:11]
	s_setprio 0
	s_setprio 1
	v_mfma_f32_16x16x32_bf16 v[52:55], v[186:189], v[202:205], v[52:55]
	v_mfma_f32_16x16x32_bf16 v[44:47], v[194:197], v[202:205], v[44:47]
	v_mfma_f32_16x16x32_bf16 v[36:39], v[186:189], v[214:217], v[36:39]
	v_mfma_f32_16x16x32_bf16 v[28:31], v[194:197], v[214:217], v[28:31]
	v_mfma_f32_16x16x32_bf16 v[20:23], v[186:189], v[222:225], v[20:23]
	v_mfma_f32_16x16x32_bf16 v[12:15], v[194:197], v[222:225], v[12:15]
	v_mfma_f32_16x16x32_bf16 v[4:7], v[186:189], v[230:233], v[4:7]
	v_mfma_f32_16x16x32_bf16 v[0:3], v[194:197], v[230:233], v[0:3]
	v_mfma_f32_16x16x32_bf16 v[52:55], v[190:193], v[210:213], v[52:55]
	v_mfma_f32_16x16x32_bf16 v[44:47], v[198:201], v[210:213], v[44:47]
	v_mfma_f32_16x16x32_bf16 v[36:39], v[190:193], v[218:221], v[36:39]
	v_mfma_f32_16x16x32_bf16 v[28:31], v[198:201], v[218:221], v[28:31]
	v_mfma_f32_16x16x32_bf16 v[20:23], v[190:193], v[226:229], v[20:23]
	v_mfma_f32_16x16x32_bf16 v[12:15], v[198:201], v[226:229], v[12:15]
	v_mfma_f32_16x16x32_bf16 v[4:7], v[190:193], v[234:237], v[4:7]
	v_mfma_f32_16x16x32_bf16 v[0:3], v[198:201], v[234:237], v[0:3]
	s_setprio 0
	s_barrier
	s_add_i32 s0, 0, 0x18000
	v_add_u32_e32 v136, s0, v158
	s_add_i32 s1, 0, 0x1c000
	ds_read_b128 v[146:149], v136
	ds_read_b128 v[150:153], v136 offset:1024
	ds_read_b128 v[178:181], v136 offset:2048
	ds_read_b128 v[182:185], v136 offset:3072
	v_add_u32_e32 v136, s1, v158
	ds_read_b128 v[186:189], v136
	ds_read_b128 v[190:193], v136 offset:1024
	ds_read_b128 v[194:197], v136 offset:2048
	ds_read_b128 v[198:201], v136 offset:3072
	s_add_u32 s52, s52, 0x40000
	s_addc_u32 s53, s53, 0
	s_mov_b32 m0, s59
	v_lshl_add_u64 v[244:245], s[52:53], 0, v[134:135]
	ds_read_b128 v[202:205], v171 offset:32768
	ds_read_b128 v[210:213], v171 offset:33792
	ds_read_b128 v[214:217], v171 offset:34816
	ds_read_b128 v[218:221], v171 offset:35840
	ds_read_b128 v[222:225], v171 offset:36864
	ds_read_b128 v[226:229], v171 offset:37888
	ds_read_b128 v[230:233], v171 offset:38912
	ds_read_b128 v[234:237], v171 offset:39936
	global_load_lds_dwordx4 v[244:245], off
	v_lshl_add_u64 v[244:245], s[52:53], 0, v[130:131]
	s_mov_b32 m0, s60
	s_nop 0
	global_load_lds_dwordx4 v[244:245], off
	s_waitcnt vmcnt(8)
	s_waitcnt lgkmcnt(0)
	s_barrier
	s_setprio 1
	s_waitcnt lgkmcnt(0)
	v_mfma_f32_16x16x32_bf16 v[124:127], v[146:149], v[202:205], v[124:127]
	v_mfma_f32_16x16x32_bf16 v[120:123], v[178:181], v[202:205], v[120:123]
	v_mfma_f32_16x16x32_bf16 v[112:115], v[146:149], v[214:217], v[112:115]
	v_mfma_f32_16x16x32_bf16 v[104:107], v[178:181], v[214:217], v[104:107]
	v_mfma_f32_16x16x32_bf16 v[96:99], v[146:149], v[222:225], v[96:99]
	v_mfma_f32_16x16x32_bf16 v[88:91], v[178:181], v[222:225], v[88:91]
	v_mfma_f32_16x16x32_bf16 v[80:83], v[146:149], v[230:233], v[80:83]
	v_mfma_f32_16x16x32_bf16 v[72:75], v[178:181], v[230:233], v[72:75]
	v_mfma_f32_16x16x32_bf16 v[124:127], v[150:153], v[210:213], v[124:127]
	v_mfma_f32_16x16x32_bf16 v[120:123], v[182:185], v[210:213], v[120:123]
	v_mfma_f32_16x16x32_bf16 v[112:115], v[150:153], v[218:221], v[112:115]
	v_mfma_f32_16x16x32_bf16 v[104:107], v[182:185], v[218:221], v[104:107]
	v_mfma_f32_16x16x32_bf16 v[96:99], v[150:153], v[226:229], v[96:99]
	v_mfma_f32_16x16x32_bf16 v[88:91], v[182:185], v[226:229], v[88:91]
	v_mfma_f32_16x16x32_bf16 v[80:83], v[150:153], v[234:237], v[80:83]
	v_mfma_f32_16x16x32_bf16 v[72:75], v[182:185], v[234:237], v[72:75]
	s_setprio 0
	s_setprio 1
	v_mfma_f32_16x16x32_bf16 v[116:119], v[186:189], v[202:205], v[116:119]
	v_mfma_f32_16x16x32_bf16 v[108:111], v[194:197], v[202:205], v[108:111]
	v_mfma_f32_16x16x32_bf16 v[100:103], v[186:189], v[214:217], v[100:103]
	v_mfma_f32_16x16x32_bf16 v[92:95], v[194:197], v[214:217], v[92:95]
	v_mfma_f32_16x16x32_bf16 v[84:87], v[186:189], v[222:225], v[84:87]
	v_mfma_f32_16x16x32_bf16 v[76:79], v[194:197], v[222:225], v[76:79]
	v_mfma_f32_16x16x32_bf16 v[68:71], v[186:189], v[230:233], v[68:71]
	v_mfma_f32_16x16x32_bf16 v[64:67], v[194:197], v[230:233], v[64:67]
	v_mfma_f32_16x16x32_bf16 v[116:119], v[190:193], v[210:213], v[116:119]
	v_mfma_f32_16x16x32_bf16 v[108:111], v[198:201], v[210:213], v[108:111]
	v_mfma_f32_16x16x32_bf16 v[100:103], v[190:193], v[218:221], v[100:103]
	v_mfma_f32_16x16x32_bf16 v[92:95], v[198:201], v[218:221], v[92:95]
	v_mfma_f32_16x16x32_bf16 v[84:87], v[190:193], v[226:229], v[84:87]
	v_mfma_f32_16x16x32_bf16 v[76:79], v[198:201], v[226:229], v[76:79]
	v_mfma_f32_16x16x32_bf16 v[68:71], v[190:193], v[234:237], v[68:71]
	v_mfma_f32_16x16x32_bf16 v[64:67], v[198:201], v[234:237], v[64:67]
	s_setprio 0
	s_barrier
; #define PG8_STAGE(bufoff, gbase, voff) do { _Pragma("unroll") for (int _i = 0; _i < 2; ++_i) \
;         __builtin_amdgcn_global_load_lds((const unsigned*)((const char*)(gbase) + (voff)[_i]), (PG8_LAS unsigned*)(lds + (bufoff) + ldsw + _i * 8192), 16, 0, 0); } while (0)
; #define PG8_LDA(dst, b, h) do { _Pragma("unroll") for (int m = 0; m < 4; ++m) _Pragma("unroll") for (int k = 0; k < 2; ++k) dst[m][k] = *(const PG8_LAS bf16x8*)(lds + PG8_SA(b, h) + aoff + m * 2048 + k * 1024); } while (0)
; #define PG8_MMA(ai, bj, At, Bt) do { __builtin_amdgcn_s_setprio(1); _Pragma("unroll") for (int m = 0; m < 4; ++m) _Pragma("unroll") for (int n = 0; n < 2; ++n) _Pragma("unroll") for (int k = 0; k < 2; ++k) \
;         acc[ai][bj][m][n] = __builtin_amdgcn_mfma_f32_16x16x32_bf16(Bt[n][k], At[m][k], acc[ai][bj][m][n], 0, 0, 0); __builtin_amdgcn_s_setprio(0); } while (0)
; #define PG8_WAIT_V(n) asm volatile("s_waitcnt vmcnt(" #n ")" ::: "memory")
; #define PG8_WAIT_L(n) asm volatile("s_waitcnt lgkmcnt(" #n ")" ::: "memory")
; #define PG8_BAR __builtin_amdgcn_s_barrier()
; #define PG8_SCHED __builtin_amdgcn_sched_barrier(0)
; template <class Epi, class Sched, bool ALIGN_EPI = false, bool SP2 = false>
; __device__ __forceinline__ void gemm_phase(PG8_LAS unsigned char* lds, const Gemm g, const Sched& S, const Epi& E) {
;     ...
;         for (int t = 0; t < nt; t += 2) {
;     ...
;             PG8_LDA(At, 1, 1); PG8_STAGE(PG8_SB(1, 0), b3, voffB); PG8_STAGE(PG8_SB(1, 1), b3 + hstep, voffB); PG8_STAGE(PG8_SA(1, 0), a3, voffA);
;             PG8_WAIT_V(8); PG8_WAIT_L(0); PG8_BAR; PG8_MMA(1, 0, At, B0); PG8_MMA(1, 1, At, B1); PG8_BAR; PG8_SCHED;
	s_add_i32 s0, s0, s29
	v_lshl_add_u64 v[206:207], v[206:207], 0, s[38:39]
	s_mov_b32 m0, s0
	ds_read_b128 v[202:205], v171 offset:49152
	ds_read_b128 v[210:213], v171 offset:50176
	ds_read_b128 v[214:217], v171 offset:51200
	ds_read_b128 v[218:221], v171 offset:52224
	ds_read_b128 v[222:225], v171 offset:53248
	ds_read_b128 v[226:229], v171 offset:54272
	ds_read_b128 v[230:233], v171 offset:55296
	ds_read_b128 v[234:237], v171 offset:56320
	global_load_lds_dwordx4 v[206:207], off
	s_add_i32 m0, s0, 0x2000
	s_add_u32 s50, s50, 0x40080
	v_lshl_add_u64 v[206:207], v[238:239], 0, s[38:39]
	s_addc_u32 s51, s51, 0
	s_add_i32 s0, s1, s29
	global_load_lds_dwordx4 v[206:207], off
	v_lshl_add_u64 v[206:207], s[50:51], 0, v[132:133]
	s_mov_b32 m0, s0
	s_nop 0
	global_load_lds_dwordx4 v[206:207], off
	v_lshl_add_u64 v[206:207], s[50:51], 0, v[128:129]
	s_add_i32 m0, s0, 0x2000
	s_nop 0
	global_load_lds_dwordx4 v[206:207], off
	v_lshl_add_u64 v[206:207], v[240:241], 0, s[38:39]
	s_mov_b32 m0, s69
	s_nop 0
	global_load_lds_dwordx4 v[206:207], off
	v_lshl_add_u64 v[206:207], v[242:243], 0, s[38:39]
	s_mov_b32 m0, s70
	s_nop 0
	global_load_lds_dwordx4 v[206:207], off
	s_waitcnt vmcnt(8)
	s_waitcnt lgkmcnt(0)
	s_barrier
	s_setprio 1
	s_waitcnt lgkmcnt(0)
	v_mfma_f32_16x16x32_bf16 v[60:63], v[146:149], v[202:205], v[60:63]
	v_mfma_f32_16x16x32_bf16 v[56:59], v[178:181], v[202:205], v[56:59]
	v_mfma_f32_16x16x32_bf16 v[48:51], v[146:149], v[214:217], v[48:51]
	v_mfma_f32_16x16x32_bf16 v[40:43], v[178:181], v[214:217], v[40:43]
	v_mfma_f32_16x16x32_bf16 v[32:35], v[146:149], v[222:225], v[32:35]
	v_mfma_f32_16x16x32_bf16 v[24:27], v[178:181], v[222:225], v[24:27]
	v_mfma_f32_16x16x32_bf16 v[16:19], v[146:149], v[230:233], v[16:19]
	v_mfma_f32_16x16x32_bf16 v[8:11], v[178:181], v[230:233], v[8:11]
	v_mfma_f32_16x16x32_bf16 v[60:63], v[150:153], v[210:213], v[60:63]
	v_mfma_f32_16x16x32_bf16 v[56:59], v[182:185], v[210:213], v[56:59]
	v_mfma_f32_16x16x32_bf16 v[48:51], v[150:153], v[218:221], v[48:51]
	v_mfma_f32_16x16x32_bf16 v[40:43], v[182:185], v[218:221], v[40:43]
	v_mfma_f32_16x16x32_bf16 v[32:35], v[150:153], v[226:229], v[32:35]
	v_mfma_f32_16x16x32_bf16 v[24:27], v[182:185], v[226:229], v[24:27]
	v_mfma_f32_16x16x32_bf16 v[16:19], v[150:153], v[234:237], v[16:19]
	v_mfma_f32_16x16x32_bf16 v[8:11], v[182:185], v[234:237], v[8:11]
	s_setprio 0
	s_setprio 1
	v_mfma_f32_16x16x32_bf16 v[52:55], v[186:189], v[202:205], v[52:55]
	v_mfma_f32_16x16x32_bf16 v[44:47], v[194:197], v[202:205], v[44:47]
	v_mfma_f32_16x16x32_bf16 v[36:39], v[186:189], v[214:217], v[36:39]
	v_mfma_f32_16x16x32_bf16 v[28:31], v[194:197], v[214:217], v[28:31]
	v_mfma_f32_16x16x32_bf16 v[20:23], v[186:189], v[222:225], v[20:23]
	v_mfma_f32_16x16x32_bf16 v[12:15], v[194:197], v[222:225], v[12:15]
	v_mfma_f32_16x16x32_bf16 v[4:7], v[186:189], v[230:233], v[4:7]
	v_mfma_f32_16x16x32_bf16 v[0:3], v[194:197], v[230:233], v[0:3]
	v_mfma_f32_16x16x32_bf16 v[52:55], v[190:193], v[210:213], v[52:55]
	v_mfma_f32_16x16x32_bf16 v[44:47], v[198:201], v[210:213], v[44:47]
	v_mfma_f32_16x16x32_bf16 v[36:39], v[190:193], v[218:221], v[36:39]
	v_mfma_f32_16x16x32_bf16 v[28:31], v[198:201], v[218:221], v[28:31]
	v_mfma_f32_16x16x32_bf16 v[20:23], v[190:193], v[226:229], v[20:23]
	v_mfma_f32_16x16x32_bf16 v[12:15], v[198:201], v[226:229], v[12:15]
	v_mfma_f32_16x16x32_bf16 v[4:7], v[190:193], v[234:237], v[4:7]
	v_mfma_f32_16x16x32_bf16 v[0:3], v[198:201], v[234:237], v[0:3]
	s_setprio 0
	s_add_i32 s93, s93, 2
	s_add_u32 s14, s14, 0x100
	s_addc_u32 s15, s15, 0
	s_add_u32 s91, s91, 0x100
	s_addc_u32 s92, s92, 0
	s_cmp_gt_u32 s93, 13
	s_cbranch_scc0 .Lkrot0
	s_barrier

; template <class Epi, class Sched, bool ALIGN_EPI = false, bool SP2 = false>
; __device__ __forceinline__ void gemm_phase(PG8_LAS unsigned char* lds, const Gemm g, const Sched& S, const Epi& E) {
;     ...
;         for (int t = 0; t < nt; t += 2) {
;             const bool last = (t == nt - 2);
.Lp2_vloop:
	s_branch .Lkbody1

; #define PG8_STAGE(bufoff, gbase, voff) do { _Pragma("unroll") for (int _i = 0; _i < 2; ++_i) \
;         __builtin_amdgcn_global_load_lds((const unsigned*)((const char*)(gbase) + (voff)[_i]), (PG8_LAS unsigned*)(lds + (bufoff) + ldsw + _i * 8192), 16, 0, 0); } while (0)
; #define PG8_LDA(dst, b, h) do { _Pragma("unroll") for (int m = 0; m < 4; ++m) _Pragma("unroll") for (int k = 0; k < 2; ++k) dst[m][k] = *(const PG8_LAS bf16x8*)(lds + PG8_SA(b, h) + aoff + m * 2048 + k * 1024); } while (0)
; #define PG8_LDB(dst, b, h) do { _Pragma("unroll") for (int n = 0; n < 2; ++n) _Pragma("unroll") for (int k = 0; k < 2; ++k) dst[n][k] = *(const PG8_LAS bf16x8*)(lds + PG8_SB(b, h) + boff + n * 2048 + k * 1024); } while (0)
; #define PG8_MMA(ai, bj, At, Bt) do { __builtin_amdgcn_s_setprio(1); _Pragma("unroll") for (int m = 0; m < 4; ++m) _Pragma("unroll") for (int n = 0; n < 2; ++n) _Pragma("unroll") for (int k = 0; k < 2; ++k) \
;         acc[ai][bj][m][n] = __builtin_amdgcn_mfma_f32_16x16x32_bf16(Bt[n][k], At[m][k], acc[ai][bj][m][n], 0, 0, 0); __builtin_amdgcn_s_setprio(0); } while (0)
; #define PG8_WAIT_V(n) asm volatile("s_waitcnt vmcnt(" #n ")" ::: "memory")
; #define PG8_WAIT_L(n) asm volatile("s_waitcnt lgkmcnt(" #n ")" ::: "memory")
; #define PG8_BAR __builtin_amdgcn_s_barrier()
; #define PG8_SCHED __builtin_amdgcn_sched_barrier(0)
; template <class Epi, class Sched, bool ALIGN_EPI = false, bool SP2 = false>
; __device__ __forceinline__ void gemm_phase(PG8_LAS unsigned char* lds, const Gemm g, const Sched& S, const Epi& E) {
;     ...
;             PG8_LDB(B0, 0, 0); PG8_LDB(B1, 0, 1); PG8_SCHED; PG8_LDA(At, 0, 0); PG8_STAGE(PG8_SA(1, 1), a1 + hstep, voffA);
;             PG8_WAIT_V(8); PG8_WAIT_L(0); PG8_BAR; PG8_MMA(0, 0, At, B0); PG8_MMA(0, 1, At, B1); PG8_BAR; PG8_SCHED;
;             PG8_LDA(At, 0, 1); PG8_STAGE(PG8_SB(0, 0), b2, voffB); PG8_STAGE(PG8_SB(0, 1), b2 + hstep, voffB); PG8_STAGE(PG8_SA(0, 0), a2, voffA);
;             PG8_WAIT_V(8); PG8_WAIT_L(0); PG8_BAR; PG8_MMA(1, 0, At, B0); PG8_MMA(1, 1, At, B1); PG8_BAR; PG8_SCHED;
.Lkbody1:
	ds_read_b128 v[146:149], v169
	ds_read_b128 v[150:153], v169 offset:1024
	ds_read_b128 v[178:181], v169 offset:2048
	ds_read_b128 v[182:185], v169 offset:3072
	ds_read_b128 v[186:189], v170
	ds_read_b128 v[190:193], v170 offset:1024
	ds_read_b128 v[194:197], v170 offset:2048
	ds_read_b128 v[198:201], v170 offset:3072
	s_add_u32 s0, s14, 0xfffc0080
	s_addc_u32 s1, s15, -1
	s_cmp_eq_u32 s93, 12
	s_cselect_b32 s53, s45, s1
	s_cselect_b32 s52, s89, s0
	s_cselect_b32 s51, s43, s92
	s_cselect_b32 s50, s90, s91
	v_lshl_add_u64 v[206:207], s[14:15], 0, v[138:139]
	s_add_i32 m0, s56, 0xc000
	ds_read_b128 v[202:205], v171
	ds_read_b128 v[210:213], v171 offset:1024
	ds_read_b128 v[214:217], v171 offset:2048
	ds_read_b128 v[218:221], v171 offset:3072
	ds_read_b128 v[222:225], v171 offset:4096
	ds_read_b128 v[226:229], v171 offset:5120
	ds_read_b128 v[230:233], v171 offset:6144
	ds_read_b128 v[234:237], v171 offset:7168
	global_load_lds_dwordx4 v[206:207], off
	v_lshl_add_u64 v[206:207], s[14:15], 0, v[140:141]
	s_add_i32 m0, s56, 0xe000
	s_nop 0
	global_load_lds_dwordx4 v[206:207], off
	s_waitcnt vmcnt(8)
	s_waitcnt lgkmcnt(0)
	s_barrier
	s_setprio 1
	s_waitcnt lgkmcnt(0)
	v_mfma_f32_16x16x32_bf16 v[124:127], v[202:205], v[146:149], v[124:127]
	v_mfma_f32_16x16x32_bf16 v[120:123], v[202:205], v[178:181], v[120:123]
	v_mfma_f32_16x16x32_bf16 v[112:115], v[214:217], v[146:149], v[112:115]
	v_mfma_f32_16x16x32_bf16 v[104:107], v[214:217], v[178:181], v[104:107]
	v_mfma_f32_16x16x32_bf16 v[96:99], v[222:225], v[146:149], v[96:99]
	v_mfma_f32_16x16x32_bf16 v[88:91], v[222:225], v[178:181], v[88:91]
	v_mfma_f32_16x16x32_bf16 v[80:83], v[230:233], v[146:149], v[80:83]
	v_mfma_f32_16x16x32_bf16 v[72:75], v[230:233], v[178:181], v[72:75]
	v_mfma_f32_16x16x32_bf16 v[124:127], v[210:213], v[150:153], v[124:127]
	v_mfma_f32_16x16x32_bf16 v[120:123], v[210:213], v[182:185], v[120:123]
	v_mfma_f32_16x16x32_bf16 v[112:115], v[218:221], v[150:153], v[112:115]
	v_mfma_f32_16x16x32_bf16 v[104:107], v[218:221], v[182:185], v[104:107]
	v_mfma_f32_16x16x32_bf16 v[96:99], v[226:229], v[150:153], v[96:99]
	v_mfma_f32_16x16x32_bf16 v[88:91], v[226:229], v[182:185], v[88:91]
	v_mfma_f32_16x16x32_bf16 v[80:83], v[234:237], v[150:153], v[80:83]
	v_mfma_f32_16x16x32_bf16 v[72:75], v[234:237], v[182:185], v[72:75]
	s_setprio 0
	s_setprio 1
	v_mfma_f32_16x16x32_bf16 v[116:119], v[202:205], v[186:189], v[116:119]
	v_mfma_f32_16x16x32_bf16 v[108:111], v[202:205], v[194:197], v[108:111]
	v_mfma_f32_16x16x32_bf16 v[100:103], v[214:217], v[186:189], v[100:103]
	v_mfma_f32_16x16x32_bf16 v[92:95], v[214:217], v[194:197], v[92:95]
	v_mfma_f32_16x16x32_bf16 v[84:87], v[222:225], v[186:189], v[84:87]
	v_mfma_f32_16x16x32_bf16 v[76:79], v[222:225], v[194:197], v[76:79]
	v_mfma_f32_16x16x32_bf16 v[68:71], v[230:233], v[186:189], v[68:71]
	v_mfma_f32_16x16x32_bf16 v[64:67], v[230:233], v[194:197], v[64:67]
	v_mfma_f32_16x16x32_bf16 v[116:119], v[210:213], v[190:193], v[116:119]
	v_mfma_f32_16x16x32_bf16 v[108:111], v[210:213], v[198:201], v[108:111]
	v_mfma_f32_16x16x32_bf16 v[100:103], v[218:221], v[190:193], v[100:103]
	v_mfma_f32_16x16x32_bf16 v[92:95], v[218:221], v[198:201], v[92:95]
	v_mfma_f32_16x16x32_bf16 v[84:87], v[226:229], v[190:193], v[84:87]
	v_mfma_f32_16x16x32_bf16 v[76:79], v[226:229], v[198:201], v[76:79]
	v_mfma_f32_16x16x32_bf16 v[68:71], v[234:237], v[190:193], v[68:71]
	v_mfma_f32_16x16x32_bf16 v[64:67], v[234:237], v[198:201], v[64:67]
	s_setprio 0
	s_barrier
	s_add_i32 s0, s74, s29
	v_lshl_add_u64 v[206:207], s[50:51], 0, v[132:133]
	s_mov_b32 m0, s0
	ds_read_b128 v[202:205], v171 offset:16384
	ds_read_b128 v[210:213], v171 offset:17408
	ds_read_b128 v[214:217], v171 offset:18432
	ds_read_b128 v[218:221], v171 offset:19456
	ds_read_b128 v[222:225], v171 offset:20480
	ds_read_b128 v[226:229], v171 offset:21504
	ds_read_b128 v[230:233], v171 offset:22528
	ds_read_b128 v[234:237], v171 offset:23552
	global_load_lds_dwordx4 v[206:207], off
	s_add_i32 m0, s0, 0x2000
	s_add_u32 s94, s50, 0x40000
	v_lshl_add_u64 v[238:239], s[50:51], 0, v[128:129]
	s_addc_u32 s95, s51, 0
	s_add_i32 s0, s75, s29
	global_load_lds_dwordx4 v[238:239], off
	v_lshl_add_u64 v[240:241], s[94:95], 0, v[132:133]
	s_mov_b32 m0, s0
	v_lshl_add_u64 v[242:243], s[52:53], 0, v[130:131]
	global_load_lds_dwordx4 v[240:241], off
	v_lshl_add_u64 v[240:241], s[94:95], 0, v[128:129]
	s_add_i32 m0, s0, 0x2000
	s_nop 0
	global_load_lds_dwordx4 v[240:241], off
	v_lshl_add_u64 v[240:241], s[52:53], 0, v[134:135]
	s_mov_b32 m0, s56
	s_nop 0
	global_load_lds_dwordx4 v[240:241], off
	s_mov_b32 m0, s57
	s_nop 0
	global_load_lds_dwordx4 v[242:243], off
	s_waitcnt vmcnt(8)
	s_waitcnt lgkmcnt(0)
	s_barrier
; #define PG8_STAGE(bufoff, gbase, voff) do { _Pragma("unroll") for (int _i = 0; _i < 2; ++_i) \
;         __builtin_amdgcn_global_load_lds((const unsigned*)((const char*)(gbase) + (voff)[_i]), (PG8_LAS unsigned*)(lds + (bufoff) + ldsw + _i * 8192), 16, 0, 0); } while (0)
; #define PG8_LDA(dst, b, h) do { _Pragma("unroll") for (int m = 0; m < 4; ++m) _Pragma("unroll") for (int k = 0; k < 2; ++k) dst[m][k] = *(const PG8_LAS bf16x8*)(lds + PG8_SA(b, h) + aoff + m * 2048 + k * 1024); } while (0)
; #define PG8_LDB(dst, b, h) do { _Pragma("unroll") for (int n = 0; n < 2; ++n) _Pragma("unroll") for (int k = 0; k < 2; ++k) dst[n][k] = *(const PG8_LAS bf16x8*)(lds + PG8_SB(b, h) + boff + n * 2048 + k * 1024); } while (0)
; #define PG8_MMA(ai, bj, At, Bt) do { __builtin_amdgcn_s_setprio(1); _Pragma("unroll") for (int m = 0; m < 4; ++m) _Pragma("unroll") for (int n = 0; n < 2; ++n) _Pragma("unroll") for (int k = 0; k < 2; ++k) \
;         acc[ai][bj][m][n] = __builtin_amdgcn_mfma_f32_16x16x32_bf16(Bt[n][k], At[m][k], acc[ai][bj][m][n], 0, 0, 0); __builtin_amdgcn_s_setprio(0); } while (0)
; #define PG8_WAIT_V(n) asm volatile("s_waitcnt vmcnt(" #n ")" ::: "memory")
; #define PG8_WAIT_L(n) asm volatile("s_waitcnt lgkmcnt(" #n ")" ::: "memory")
; #define PG8_BAR __builtin_amdgcn_s_barrier()
; #define PG8_SCHED __builtin_amdgcn_sched_barrier(0)
; template <class Epi, class Sched, bool ALIGN_EPI = false, bool SP2 = false>
; __device__ __forceinline__ void gemm_phase(PG8_LAS unsigned char* lds, const Gemm g, const Sched& S, const Epi& E) {
;     ...
;             PG8_WAIT_V(8); PG8_WAIT_L(0); PG8_BAR; PG8_MMA(1, 0, At, B0); PG8_MMA(1, 1, At, B1); PG8_BAR; PG8_SCHED;
;             PG8_LDB(B0, 1, 0); PG8_LDB(B1, 1, 1); PG8_SCHED; PG8_LDA(At, 1, 0); PG8_STAGE(PG8_SA(0, 1), a2 + hstep, voffA);
;             PG8_WAIT_V(8); PG8_WAIT_L(0); PG8_BAR; PG8_MMA(0, 0, At, B0); PG8_MMA(0, 1, At, B1); PG8_BAR; PG8_SCHED;
	s_setprio 1
	s_waitcnt lgkmcnt(0)
	v_mfma_f32_16x16x32_bf16 v[60:63], v[202:205], v[146:149], v[60:63]
	v_mfma_f32_16x16x32_bf16 v[56:59], v[202:205], v[178:181], v[56:59]
	v_mfma_f32_16x16x32_bf16 v[48:51], v[214:217], v[146:149], v[48:51]
	v_mfma_f32_16x16x32_bf16 v[40:43], v[214:217], v[178:181], v[40:43]
	v_mfma_f32_16x16x32_bf16 v[32:35], v[222:225], v[146:149], v[32:35]
	v_mfma_f32_16x16x32_bf16 v[24:27], v[222:225], v[178:181], v[24:27]
	v_mfma_f32_16x16x32_bf16 v[16:19], v[230:233], v[146:149], v[16:19]
	v_mfma_f32_16x16x32_bf16 v[8:11], v[230:233], v[178:181], v[8:11]
	v_mfma_f32_16x16x32_bf16 v[60:63], v[210:213], v[150:153], v[60:63]
	v_mfma_f32_16x16x32_bf16 v[56:59], v[210:213], v[182:185], v[56:59]
	v_mfma_f32_16x16x32_bf16 v[48:51], v[218:221], v[150:153], v[48:51]
	v_mfma_f32_16x16x32_bf16 v[40:43], v[218:221], v[182:185], v[40:43]
	v_mfma_f32_16x16x32_bf16 v[32:35], v[226:229], v[150:153], v[32:35]
	v_mfma_f32_16x16x32_bf16 v[24:27], v[226:229], v[182:185], v[24:27]
	v_mfma_f32_16x16x32_bf16 v[16:19], v[234:237], v[150:153], v[16:19]
	v_mfma_f32_16x16x32_bf16 v[8:11], v[234:237], v[182:185], v[8:11]
	s_setprio 0
	s_setprio 1
	v_mfma_f32_16x16x32_bf16 v[52:55], v[202:205], v[186:189], v[52:55]
	v_mfma_f32_16x16x32_bf16 v[44:47], v[202:205], v[194:197], v[44:47]
	v_mfma_f32_16x16x32_bf16 v[36:39], v[214:217], v[186:189], v[36:39]
	v_mfma_f32_16x16x32_bf16 v[28:31], v[214:217], v[194:197], v[28:31]
	v_mfma_f32_16x16x32_bf16 v[20:23], v[222:225], v[186:189], v[20:23]
	v_mfma_f32_16x16x32_bf16 v[12:15], v[222:225], v[194:197], v[12:15]
	v_mfma_f32_16x16x32_bf16 v[4:7], v[230:233], v[186:189], v[4:7]
	v_mfma_f32_16x16x32_bf16 v[0:3], v[230:233], v[194:197], v[0:3]
	v_mfma_f32_16x16x32_bf16 v[52:55], v[210:213], v[190:193], v[52:55]
	v_mfma_f32_16x16x32_bf16 v[44:47], v[210:213], v[198:201], v[44:47]
	v_mfma_f32_16x16x32_bf16 v[36:39], v[218:221], v[190:193], v[36:39]
	v_mfma_f32_16x16x32_bf16 v[28:31], v[218:221], v[198:201], v[28:31]
	v_mfma_f32_16x16x32_bf16 v[20:23], v[226:229], v[190:193], v[20:23]
	v_mfma_f32_16x16x32_bf16 v[12:15], v[226:229], v[198:201], v[12:15]
	v_mfma_f32_16x16x32_bf16 v[4:7], v[234:237], v[190:193], v[4:7]
	v_mfma_f32_16x16x32_bf16 v[0:3], v[234:237], v[198:201], v[0:3]
	s_setprio 0
	s_barrier
	s_add_i32 s0, 0, 0x18000
	v_add_u32_e32 v136, s0, v158
	s_add_i32 s1, 0, 0x1c000
	ds_read_b128 v[146:149], v136
	ds_read_b128 v[150:153], v136 offset:1024
	ds_read_b128 v[178:181], v136 offset:2048
	ds_read_b128 v[182:185], v136 offset:3072
	v_add_u32_e32 v136, s1, v158
	ds_read_b128 v[186:189], v136
	ds_read_b128 v[190:193], v136 offset:1024
	ds_read_b128 v[194:197], v136 offset:2048
	ds_read_b128 v[198:201], v136 offset:3072
	s_add_u32 s52, s52, 0x40000
	s_addc_u32 s53, s53, 0
	s_mov_b32 m0, s59
	v_lshl_add_u64 v[244:245], s[52:53], 0, v[134:135]
	ds_read_b128 v[202:205], v171 offset:32768
	ds_read_b128 v[210:213], v171 offset:33792
	ds_read_b128 v[214:217], v171 offset:34816
	ds_read_b128 v[218:221], v171 offset:35840
	ds_read_b128 v[222:225], v171 offset:36864
	ds_read_b128 v[226:229], v171 offset:37888
	ds_read_b128 v[230:233], v171 offset:38912
	ds_read_b128 v[234:237], v171 offset:39936
	global_load_lds_dwordx4 v[244:245], off
	v_lshl_add_u64 v[244:245], s[52:53], 0, v[130:131]
	s_mov_b32 m0, s60
	s_nop 0
	global_load_lds_dwordx4 v[244:245], off
	s_waitcnt vmcnt(8)
	s_waitcnt lgkmcnt(0)
	s_barrier
	s_setprio 1
	s_waitcnt lgkmcnt(0)
	v_mfma_f32_16x16x32_bf16 v[124:127], v[202:205], v[146:149], v[124:127]
	v_mfma_f32_16x16x32_bf16 v[120:123], v[202:205], v[178:181], v[120:123]
	v_mfma_f32_16x16x32_bf16 v[112:115], v[214:217], v[146:149], v[112:115]
	v_mfma_f32_16x16x32_bf16 v[104:107], v[214:217], v[178:181], v[104:107]
	v_mfma_f32_16x16x32_bf16 v[96:99], v[222:225], v[146:149], v[96:99]
	v_mfma_f32_16x16x32_bf16 v[88:91], v[222:225], v[178:181], v[88:91]
	v_mfma_f32_16x16x32_bf16 v[80:83], v[230:233], v[146:149], v[80:83]
	v_mfma_f32_16x16x32_bf16 v[72:75], v[230:233], v[178:181], v[72:75]
	v_mfma_f32_16x16x32_bf16 v[124:127], v[210:213], v[150:153], v[124:127]
	v_mfma_f32_16x16x32_bf16 v[120:123], v[210:213], v[182:185], v[120:123]
	v_mfma_f32_16x16x32_bf16 v[112:115], v[218:221], v[150:153], v[112:115]
	v_mfma_f32_16x16x32_bf16 v[104:107], v[218:221], v[182:185], v[104:107]
	v_mfma_f32_16x16x32_bf16 v[96:99], v[226:229], v[150:153], v[96:99]
	v_mfma_f32_16x16x32_bf16 v[88:91], v[226:229], v[182:185], v[88:91]
	v_mfma_f32_16x16x32_bf16 v[80:83], v[234:237], v[150:153], v[80:83]
	v_mfma_f32_16x16x32_bf16 v[72:75], v[234:237], v[182:185], v[72:75]
	s_setprio 0
	s_setprio 1
	v_mfma_f32_16x16x32_bf16 v[116:119], v[202:205], v[186:189], v[116:119]
	v_mfma_f32_16x16x32_bf16 v[108:111], v[202:205], v[194:197], v[108:111]
	v_mfma_f32_16x16x32_bf16 v[100:103], v[214:217], v[186:189], v[100:103]
	v_mfma_f32_16x16x32_bf16 v[92:95], v[214:217], v[194:197], v[92:95]
	v_mfma_f32_16x16x32_bf16 v[84:87], v[222:225], v[186:189], v[84:87]
	v_mfma_f32_16x16x32_bf16 v[76:79], v[222:225], v[194:197], v[76:79]
	v_mfma_f32_16x16x32_bf16 v[68:71], v[230:233], v[186:189], v[68:71]
	v_mfma_f32_16x16x32_bf16 v[64:67], v[230:233], v[194:197], v[64:67]
	v_mfma_f32_16x16x32_bf16 v[116:119], v[210:213], v[190:193], v[116:119]
	v_mfma_f32_16x16x32_bf16 v[108:111], v[210:213], v[198:201], v[108:111]
	v_mfma_f32_16x16x32_bf16 v[100:103], v[218:221], v[190:193], v[100:103]
	v_mfma_f32_16x16x32_bf16 v[92:95], v[218:221], v[198:201], v[92:95]
	v_mfma_f32_16x16x32_bf16 v[84:87], v[226:229], v[190:193], v[84:87]
	v_mfma_f32_16x16x32_bf16 v[76:79], v[226:229], v[198:201], v[76:79]
	v_mfma_f32_16x16x32_bf16 v[68:71], v[234:237], v[190:193], v[68:71]
	v_mfma_f32_16x16x32_bf16 v[64:67], v[234:237], v[198:201], v[64:67]
	s_setprio 0
	s_barrier
; #define PG8_STAGE(bufoff, gbase, voff) do { _Pragma("unroll") for (int _i = 0; _i < 2; ++_i) \
;         __builtin_amdgcn_global_load_lds((const unsigned*)((const char*)(gbase) + (voff)[_i]), (PG8_LAS unsigned*)(lds + (bufoff) + ldsw + _i * 8192), 16, 0, 0); } while (0)
; #define PG8_LDA(dst, b, h) do { _Pragma("unroll") for (int m = 0; m < 4; ++m) _Pragma("unroll") for (int k = 0; k < 2; ++k) dst[m][k] = *(const PG8_LAS bf16x8*)(lds + PG8_SA(b, h) + aoff + m * 2048 + k * 1024); } while (0)
; #define PG8_MMA(ai, bj, At, Bt) do { __builtin_amdgcn_s_setprio(1); _Pragma("unroll") for (int m = 0; m < 4; ++m) _Pragma("unroll") for (int n = 0; n < 2; ++n) _Pragma("unroll") for (int k = 0; k < 2; ++k) \
;         acc[ai][bj][m][n] = __builtin_amdgcn_mfma_f32_16x16x32_bf16(Bt[n][k], At[m][k], acc[ai][bj][m][n], 0, 0, 0); __builtin_amdgcn_s_setprio(0); } while (0)
; #define PG8_WAIT_V(n) asm volatile("s_waitcnt vmcnt(" #n ")" ::: "memory")
; #define PG8_WAIT_L(n) asm volatile("s_waitcnt lgkmcnt(" #n ")" ::: "memory")
; #define PG8_BAR __builtin_amdgcn_s_barrier()
; #define PG8_SCHED __builtin_amdgcn_sched_barrier(0)
; template <class Epi, class Sched, bool ALIGN_EPI = false, bool SP2 = false>
; __device__ __forceinline__ void gemm_phase(PG8_LAS unsigned char* lds, const Gemm g, const Sched& S, const Epi& E) {
;     ...
;         for (int t = 0; t < nt; t += 2) {
;     ...
;             PG8_LDA(At, 1, 1); PG8_STAGE(PG8_SB(1, 0), b3, voffB); PG8_STAGE(PG8_SB(1, 1), b3 + hstep, voffB); PG8_STAGE(PG8_SA(1, 0), a3, voffA);
;             PG8_WAIT_V(8); PG8_WAIT_L(0); PG8_BAR; PG8_MMA(1, 0, At, B0); PG8_MMA(1, 1, At, B1); PG8_BAR; PG8_SCHED;
	s_add_i32 s0, s0, s29
	v_lshl_add_u64 v[206:207], v[206:207], 0, s[38:39]
	s_mov_b32 m0, s0
	ds_read_b128 v[202:205], v171 offset:49152
	ds_read_b128 v[210:213], v171 offset:50176
	ds_read_b128 v[214:217], v171 offset:51200
	ds_read_b128 v[218:221], v171 offset:52224
	ds_read_b128 v[222:225], v171 offset:53248
	ds_read_b128 v[226:229], v171 offset:54272
	ds_read_b128 v[230:233], v171 offset:55296
	ds_read_b128 v[234:237], v171 offset:56320
	global_load_lds_dwordx4 v[206:207], off
	s_add_i32 m0, s0, 0x2000
	s_add_u32 s50, s50, 0x40080
	v_lshl_add_u64 v[206:207], v[238:239], 0, s[38:39]
	s_addc_u32 s51, s51, 0
	s_add_i32 s0, s1, s29
	global_load_lds_dwordx4 v[206:207], off
	v_lshl_add_u64 v[206:207], s[50:51], 0, v[132:133]
	s_mov_b32 m0, s0
	s_nop 0
	global_load_lds_dwordx4 v[206:207], off
	v_lshl_add_u64 v[206:207], s[50:51], 0, v[128:129]
	s_add_i32 m0, s0, 0x2000
	s_nop 0
	global_load_lds_dwordx4 v[206:207], off
	v_lshl_add_u64 v[206:207], v[240:241], 0, s[38:39]
	s_mov_b32 m0, s69
	s_nop 0
	global_load_lds_dwordx4 v[206:207], off
	v_lshl_add_u64 v[206:207], v[242:243], 0, s[38:39]
	s_mov_b32 m0, s70
	s_nop 0
	global_load_lds_dwordx4 v[206:207], off
	s_waitcnt vmcnt(8)
	s_waitcnt lgkmcnt(0)
	s_barrier
	s_setprio 1
	s_waitcnt lgkmcnt(0)
	v_mfma_f32_16x16x32_bf16 v[60:63], v[202:205], v[146:149], v[60:63]
	v_mfma_f32_16x16x32_bf16 v[56:59], v[202:205], v[178:181], v[56:59]
	v_mfma_f32_16x16x32_bf16 v[48:51], v[214:217], v[146:149], v[48:51]
	v_mfma_f32_16x16x32_bf16 v[40:43], v[214:217], v[178:181], v[40:43]
	v_mfma_f32_16x16x32_bf16 v[32:35], v[222:225], v[146:149], v[32:35]
	v_mfma_f32_16x16x32_bf16 v[24:27], v[222:225], v[178:181], v[24:27]
	v_mfma_f32_16x16x32_bf16 v[16:19], v[230:233], v[146:149], v[16:19]
	v_mfma_f32_16x16x32_bf16 v[8:11], v[230:233], v[178:181], v[8:11]
	v_mfma_f32_16x16x32_bf16 v[60:63], v[210:213], v[150:153], v[60:63]
	v_mfma_f32_16x16x32_bf16 v[56:59], v[210:213], v[182:185], v[56:59]
	v_mfma_f32_16x16x32_bf16 v[48:51], v[218:221], v[150:153], v[48:51]
	v_mfma_f32_16x16x32_bf16 v[40:43], v[218:221], v[182:185], v[40:43]
	v_mfma_f32_16x16x32_bf16 v[32:35], v[226:229], v[150:153], v[32:35]
	v_mfma_f32_16x16x32_bf16 v[24:27], v[226:229], v[182:185], v[24:27]
	v_mfma_f32_16x16x32_bf16 v[16:19], v[234:237], v[150:153], v[16:19]
	v_mfma_f32_16x16x32_bf16 v[8:11], v[234:237], v[182:185], v[8:11]
	s_setprio 0
	s_setprio 1
	v_mfma_f32_16x16x32_bf16 v[52:55], v[202:205], v[186:189], v[52:55]
	v_mfma_f32_16x16x32_bf16 v[44:47], v[202:205], v[194:197], v[44:47]
	v_mfma_f32_16x16x32_bf16 v[36:39], v[214:217], v[186:189], v[36:39]
	v_mfma_f32_16x16x32_bf16 v[28:31], v[214:217], v[194:197], v[28:31]
	v_mfma_f32_16x16x32_bf16 v[20:23], v[222:225], v[186:189], v[20:23]
	v_mfma_f32_16x16x32_bf16 v[12:15], v[222:225], v[194:197], v[12:15]
	v_mfma_f32_16x16x32_bf16 v[4:7], v[230:233], v[186:189], v[4:7]
	v_mfma_f32_16x16x32_bf16 v[0:3], v[230:233], v[194:197], v[0:3]
	v_mfma_f32_16x16x32_bf16 v[52:55], v[210:213], v[190:193], v[52:55]
	v_mfma_f32_16x16x32_bf16 v[44:47], v[210:213], v[198:201], v[44:47]
	v_mfma_f32_16x16x32_bf16 v[36:39], v[218:221], v[190:193], v[36:39]
	v_mfma_f32_16x16x32_bf16 v[28:31], v[218:221], v[198:201], v[28:31]
	v_mfma_f32_16x16x32_bf16 v[20:23], v[226:229], v[190:193], v[20:23]
	v_mfma_f32_16x16x32_bf16 v[12:15], v[226:229], v[198:201], v[12:15]
	v_mfma_f32_16x16x32_bf16 v[4:7], v[234:237], v[190:193], v[4:7]
	v_mfma_f32_16x16x32_bf16 v[0:3], v[234:237], v[198:201], v[0:3]
	s_setprio 0
	s_add_i32 s93, s93, 2
	s_add_u32 s14, s14, 0x100
	s_addc_u32 s15, s15, 0
	s_add_u32 s91, s91, 0x100
	s_addc_u32 s92, s92, 0
	s_cmp_gt_u32 s93, 13
	s_cbranch_scc0 .Lkrot1
	s_barrier
	s_branch .Lp2_kexit

;     __device__ __forceinline__ long a_off(int pm, size_t tstep) const { return (long)pm * (long)tstep; }
; template <class Epi, class Sched, bool ALIGN_EPI = false, bool SP2 = false>
; __device__ __forceinline__ void gemm_phase(PG8_LAS unsigned char* lds, const Gemm g, const Sched& S, const Epi& E) {
;     ...
;         const bool has_next = S.next(ui + 1, nxt);
;         const char* nA = has_next ? (const char*)g.A + S.a_off(nxt.pm, tstep) : cA; const char* nB = has_next ? (const char*)g.Bt + (size_t)nxt.pn * tstep : cB;
;     ...
; #pragma unroll
;         for (int a = 0; a < 2; ++a)
; #pragma unroll
;             for (int b = 0; b < 2; ++b)
; #pragma unroll
;                 for (int m = 0; m < 4; ++m)
; #pragma unroll
;                     for (int n = 0; n < 2; ++n) acc[a][b][m][n] = (f32x4){0.f, 0.f, 0.f, 0.f};
.LBB0_457:
	s_ashr_i32 s49, s48, 31
	s_lshl_b64 s[50:51], s[48:49], 19
	s_add_u32 s50, s3, s50
	s_addc_u32 s51, s4, s51
	s_and_b64 s[52:53], s[10:11], exec
	s_cselect_b32 s15, s51, s55
	s_cselect_b32 s23, s50, s54
	s_ashr_i32 s47, s46, 31
	s_lshl_b64 s[52:53], s[46:47], 19
	s_add_u32 s52, s5, s52
	s_addc_u32 s53, s6, s53
	s_and_b64 s[58:59], s[10:11], exec
	s_cselect_b32 s47, s53, s57
	s_cselect_b32 s49, s52, s56
	s_add_u32 s54, s54, 0x40080
	s_addc_u32 s55, s55, 0
	s_add_u32 s75, s56, 0x100
	v_mov_b32_e32 v0, 0
	s_addc_u32 s76, s57, 0
	s_mov_b32 s77, -2
	s_waitcnt lgkmcnt(0)
	v_mov_b32_e32 v1, v0
	v_mov_b32_e32 v2, v0
	v_mov_b32_e32 v3, v0
	v_mov_b32_e32 v4, v0
	v_mov_b32_e32 v5, v0
	v_mov_b32_e32 v6, v0
	v_mov_b32_e32 v7, v0
	v_mov_b32_e32 v16, v0
	v_mov_b32_e32 v17, v0
	v_mov_b32_e32 v18, v0
	v_mov_b32_e32 v19, v0
	v_mov_b32_e32 v20, v0
	v_mov_b32_e32 v21, v0
	v_mov_b32_e32 v22, v0
	v_mov_b32_e32 v23, v0
	v_mov_b32_e32 v32, v0
	v_mov_b32_e32 v33, v0
	v_mov_b32_e32 v34, v0
	v_mov_b32_e32 v35, v0
	v_mov_b32_e32 v36, v0
	v_mov_b32_e32 v37, v0
	v_mov_b32_e32 v38, v0
	v_mov_b32_e32 v39, v0
	v_mov_b32_e32 v48, v0
	v_mov_b32_e32 v49, v0
	v_mov_b32_e32 v50, v0
	v_mov_b32_e32 v51, v0
	v_mov_b32_e32 v52, v0
	v_mov_b32_e32 v53, v0
	v_mov_b32_e32 v54, v0
	v_mov_b32_e32 v55, v0
	v_mov_b32_e32 v8, v0
	v_mov_b32_e32 v9, v0
	v_mov_b32_e32 v10, v0
	v_mov_b32_e32 v11, v0
	v_mov_b32_e32 v12, v0
	v_mov_b32_e32 v13, v0
	v_mov_b32_e32 v14, v0
	v_mov_b32_e32 v15, v0
	v_mov_b32_e32 v24, v0
	v_mov_b32_e32 v25, v0
	v_mov_b32_e32 v26, v0
	v_mov_b32_e32 v27, v0
	v_mov_b32_e32 v28, v0
	v_mov_b32_e32 v29, v0
	v_mov_b32_e32 v30, v0
	v_mov_b32_e32 v31, v0
	v_mov_b32_e32 v40, v0
	v_mov_b32_e32 v41, v0
	v_mov_b32_e32 v42, v0
	v_mov_b32_e32 v43, v0
	v_mov_b32_e32 v44, v0
	v_mov_b32_e32 v45, v0
	v_mov_b32_e32 v46, v0
	v_mov_b32_e32 v47, v0
	v_mov_b32_e32 v56, v0
	v_mov_b32_e32 v57, v0
	v_mov_b32_e32 v58, v0
	v_mov_b32_e32 v59, v0
	v_mov_b32_e32 v60, v0
	v_mov_b32_e32 v61, v0
	v_mov_b32_e32 v62, v0
	v_mov_b32_e32 v63, v0
	v_mov_b32_e32 v72, v0
	v_mov_b32_e32 v73, v0
	v_mov_b32_e32 v74, v0
	v_mov_b32_e32 v75, v0
	v_mov_b32_e32 v84, v0
	v_mov_b32_e32 v85, v0
	v_mov_b32_e32 v86, v0
	v_mov_b32_e32 v87, v0
	v_mov_b32_e32 v96, v0
	v_mov_b32_e32 v97, v0
	v_mov_b32_e32 v98, v0
	v_mov_b32_e32 v99, v0
	v_mov_b32_e32 v100, v0
	v_mov_b32_e32 v101, v0
	v_mov_b32_e32 v102, v0
	v_mov_b32_e32 v103, v0
	v_mov_b32_e32 v112, v0
	v_mov_b32_e32 v113, v0
	v_mov_b32_e32 v114, v0
	v_mov_b32_e32 v115, v0
	v_mov_b32_e32 v116, v0
	v_mov_b32_e32 v117, v0
	v_mov_b32_e32 v118, v0
	v_mov_b32_e32 v119, v0
	v_mov_b32_e32 v128, v0
	v_mov_b32_e32 v129, v0
	v_mov_b32_e32 v130, v0
	v_mov_b32_e32 v131, v0
	v_mov_b32_e32 v132, v0
	v_mov_b32_e32 v133, v0
	v_mov_b32_e32 v134, v0
	v_mov_b32_e32 v135, v0
	v_mov_b32_e32 v88, v0
	v_mov_b32_e32 v89, v0
	v_mov_b32_e32 v90, v0
	v_mov_b32_e32 v91, v0
	v_mov_b32_e32 v92, v0
	v_mov_b32_e32 v93, v0
	v_mov_b32_e32 v94, v0
	v_mov_b32_e32 v95, v0
	v_mov_b32_e32 v104, v0
	v_mov_b32_e32 v105, v0
	v_mov_b32_e32 v106, v0
	v_mov_b32_e32 v107, v0
	v_mov_b32_e32 v108, v0
	v_mov_b32_e32 v109, v0
	v_mov_b32_e32 v110, v0
	v_mov_b32_e32 v111, v0
	v_mov_b32_e32 v120, v0
	v_mov_b32_e32 v121, v0
	v_mov_b32_e32 v122, v0
	v_mov_b32_e32 v123, v0
	v_mov_b32_e32 v124, v0
	v_mov_b32_e32 v125, v0
	v_mov_b32_e32 v126, v0
	v_mov_b32_e32 v127, v0
	v_mov_b32_e32 v136, v0
	v_mov_b32_e32 v137, v0
	v_mov_b32_e32 v138, v0
	v_mov_b32_e32 v139, v0
	v_mov_b32_e32 v140, v0
	v_mov_b32_e32 v141, v0
	v_mov_b32_e32 v142, v0
	v_mov_b32_e32 v143, v0
	s_branch .LBB0_458

; #define PG8_STAGE(bufoff, gbase, voff) do { _Pragma("unroll") for (int _i = 0; _i < 2; ++_i) \
;         __builtin_amdgcn_global_load_lds((const unsigned*)((const char*)(gbase) + (voff)[_i]), (PG8_LAS unsigned*)(lds + (bufoff) + ldsw + _i * 8192), 16, 0, 0); } while (0)
; #define PG8_LDA(dst, b, h) do { _Pragma("unroll") for (int m = 0; m < 4; ++m) _Pragma("unroll") for (int k = 0; k < 2; ++k) dst[m][k] = *(const PG8_LAS bf16x8*)(lds + PG8_SA(b, h) + aoff + m * 2048 + k * 1024); } while (0)
; #define PG8_LDB(dst, b, h) do { _Pragma("unroll") for (int n = 0; n < 2; ++n) _Pragma("unroll") for (int k = 0; k < 2; ++k) dst[n][k] = *(const PG8_LAS bf16x8*)(lds + PG8_SB(b, h) + boff + n * 2048 + k * 1024); } while (0)
; #define PG8_MMA(ai, bj, At, Bt) do { __builtin_amdgcn_s_setprio(1); _Pragma("unroll") for (int m = 0; m < 4; ++m) _Pragma("unroll") for (int n = 0; n < 2; ++n) _Pragma("unroll") for (int k = 0; k < 2; ++k) \
;         acc[ai][bj][m][n] = __builtin_amdgcn_mfma_f32_16x16x32_bf16(Bt[n][k], At[m][k], acc[ai][bj][m][n], 0, 0, 0); __builtin_amdgcn_s_setprio(0); } while (0)
; #define PG8_WAIT_V(n) asm volatile("s_waitcnt vmcnt(" #n ")" ::: "memory")
; #define PG8_WAIT_L(n) asm volatile("s_waitcnt lgkmcnt(" #n ")" ::: "memory")
; #define PG8_BAR __builtin_amdgcn_s_barrier()
; #define PG8_SCHED __builtin_amdgcn_sched_barrier(0)
; template <class Epi, class Sched, bool ALIGN_EPI = false, bool SP2 = false>
; __device__ __forceinline__ void gemm_phase(PG8_LAS unsigned char* lds, const Gemm g, const Sched& S, const Epi& E) {
;     ...
;             PG8_LDB(B0, 0, 0); PG8_LDB(B1, 0, 1); PG8_SCHED; PG8_LDA(At, 0, 0); PG8_STAGE(PG8_SA(1, 1), a1 + hstep, voffA);
;             PG8_WAIT_V(8); PG8_WAIT_L(0); PG8_BAR; PG8_MMA(0, 0, At, B0); PG8_MMA(0, 1, At, B1); PG8_BAR; PG8_SCHED;
;             PG8_LDA(At, 0, 1); PG8_STAGE(PG8_SB(0, 0), b2, voffB); PG8_STAGE(PG8_SB(0, 1), b2 + hstep, voffB); PG8_STAGE(PG8_SA(0, 0), a2, voffA);
;             PG8_WAIT_V(8); PG8_WAIT_L(0); PG8_BAR; PG8_MMA(1, 0, At, B0); PG8_MMA(1, 1, At, B1); PG8_BAR; PG8_SCHED;
.LBB0_458:
	ds_read_b128 v[64:67], v249
	ds_read_b128 v[68:71], v249 offset:1024
	ds_read_b128 v[76:79], v249 offset:2048
	ds_read_b128 v[80:83], v249 offset:3072
	ds_read_b128 v[144:147], v250
	ds_read_b128 v[148:151], v250 offset:1024
	ds_read_b128 v[152:155], v250 offset:2048
	ds_read_b128 v[156:159], v250 offset:3072
	s_add_u32 s0, s54, 0xfffc0080
	s_addc_u32 s1, s55, -1
	s_cmp_eq_u32 s77, 12
	s_cselect_b32 s59, s15, s1
	s_cselect_b32 s58, s23, s0
	s_cselect_b32 s57, s47, s76
	s_cselect_b32 s56, s49, s75
	v_lshl_add_u64 v[192:193], s[54:55], 0, v[220:221]
	s_add_i32 m0, s28, 0xc000
	ds_read_b128 v[160:163], v251
	ds_read_b128 v[164:167], v251 offset:1024
	ds_read_b128 v[168:171], v251 offset:2048
	ds_read_b128 v[172:175], v251 offset:3072
	ds_read_b128 v[176:179], v251 offset:4096
	ds_read_b128 v[180:183], v251 offset:5120
	ds_read_b128 v[184:187], v251 offset:6144
	ds_read_b128 v[188:191], v251 offset:7168
	global_load_lds_dwordx4 v[192:193], off
	v_lshl_add_u64 v[192:193], s[54:55], 0, v[222:223]
	s_add_i32 m0, s28, 0xe000
	s_nop 0
	global_load_lds_dwordx4 v[192:193], off
	s_waitcnt vmcnt(8)
	s_waitcnt lgkmcnt(0)
	s_barrier
	s_setprio 1
	s_waitcnt lgkmcnt(0)
	v_mfma_f32_16x16x32_bf16 v[140:143], v[64:67], v[160:163], v[140:143]
	v_mfma_f32_16x16x32_bf16 v[136:139], v[76:79], v[160:163], v[136:139]
	v_mfma_f32_16x16x32_bf16 v[124:127], v[64:67], v[168:171], v[124:127]
	v_mfma_f32_16x16x32_bf16 v[120:123], v[76:79], v[168:171], v[120:123]
	v_mfma_f32_16x16x32_bf16 v[108:111], v[64:67], v[176:179], v[108:111]
	v_mfma_f32_16x16x32_bf16 v[104:107], v[76:79], v[176:179], v[104:107]
	v_mfma_f32_16x16x32_bf16 v[92:95], v[64:67], v[184:187], v[92:95]
	v_mfma_f32_16x16x32_bf16 v[88:91], v[76:79], v[184:187], v[88:91]
	v_mfma_f32_16x16x32_bf16 v[140:143], v[68:71], v[164:167], v[140:143]
	v_mfma_f32_16x16x32_bf16 v[136:139], v[80:83], v[164:167], v[136:139]
	v_mfma_f32_16x16x32_bf16 v[124:127], v[68:71], v[172:175], v[124:127]
	v_mfma_f32_16x16x32_bf16 v[120:123], v[80:83], v[172:175], v[120:123]
	v_mfma_f32_16x16x32_bf16 v[108:111], v[68:71], v[180:183], v[108:111]
	v_mfma_f32_16x16x32_bf16 v[104:107], v[80:83], v[180:183], v[104:107]
	v_mfma_f32_16x16x32_bf16 v[92:95], v[68:71], v[188:191], v[92:95]
	v_mfma_f32_16x16x32_bf16 v[88:91], v[80:83], v[188:191], v[88:91]
	s_setprio 0
	s_setprio 1
	v_mfma_f32_16x16x32_bf16 v[132:135], v[144:147], v[160:163], v[132:135]
	v_mfma_f32_16x16x32_bf16 v[128:131], v[152:155], v[160:163], v[128:131]
	v_mfma_f32_16x16x32_bf16 v[116:119], v[144:147], v[168:171], v[116:119]
	v_mfma_f32_16x16x32_bf16 v[112:115], v[152:155], v[168:171], v[112:115]
	v_mfma_f32_16x16x32_bf16 v[100:103], v[144:147], v[176:179], v[100:103]
	v_mfma_f32_16x16x32_bf16 v[96:99], v[152:155], v[176:179], v[96:99]
	v_mfma_f32_16x16x32_bf16 v[84:87], v[144:147], v[184:187], v[84:87]
	v_mfma_f32_16x16x32_bf16 v[72:75], v[152:155], v[184:187], v[72:75]
	v_mfma_f32_16x16x32_bf16 v[132:135], v[148:151], v[164:167], v[132:135]
	v_mfma_f32_16x16x32_bf16 v[128:131], v[156:159], v[164:167], v[128:131]
	v_mfma_f32_16x16x32_bf16 v[116:119], v[148:151], v[172:175], v[116:119]
	v_mfma_f32_16x16x32_bf16 v[112:115], v[156:159], v[172:175], v[112:115]
	v_mfma_f32_16x16x32_bf16 v[100:103], v[148:151], v[180:183], v[100:103]
	v_mfma_f32_16x16x32_bf16 v[96:99], v[156:159], v[180:183], v[96:99]
	v_mfma_f32_16x16x32_bf16 v[84:87], v[148:151], v[188:191], v[84:87]
	v_mfma_f32_16x16x32_bf16 v[72:75], v[156:159], v[188:191], v[72:75]
	s_setprio 0
	s_barrier
	s_add_i32 s0, s70, s7
	v_lshl_add_u64 v[192:193], s[56:57], 0, v[212:213]
	s_mov_b32 m0, s0
	ds_read_b128 v[160:163], v251 offset:16384
	ds_read_b128 v[164:167], v251 offset:17408
	ds_read_b128 v[168:171], v251 offset:18432
	ds_read_b128 v[172:175], v251 offset:19456
	ds_read_b128 v[176:179], v251 offset:20480
	ds_read_b128 v[180:183], v251 offset:21504
	ds_read_b128 v[184:187], v251 offset:22528
	ds_read_b128 v[188:191], v251 offset:23552
	global_load_lds_dwordx4 v[192:193], off
	s_add_i32 m0, s0, 0x2000
	s_add_u32 s78, s56, 0x40000
	v_lshl_add_u64 v[194:195], s[56:57], 0, v[216:217]
	s_addc_u32 s79, s57, 0
	s_add_i32 s0, s71, s7
	global_load_lds_dwordx4 v[194:195], off
	v_lshl_add_u64 v[196:197], s[78:79], 0, v[212:213]
	s_mov_b32 m0, s0
	v_lshl_add_u64 v[198:199], s[58:59], 0, v[214:215]
	global_load_lds_dwordx4 v[196:197], off
	v_lshl_add_u64 v[196:197], s[78:79], 0, v[216:217]
	s_add_i32 m0, s0, 0x2000
	s_nop 0
	global_load_lds_dwordx4 v[196:197], off
	v_lshl_add_u64 v[196:197], s[58:59], 0, v[210:211]
	s_mov_b32 m0, s28
	s_nop 0
	global_load_lds_dwordx4 v[196:197], off
	s_mov_b32 m0, s29
	s_nop 0
	global_load_lds_dwordx4 v[198:199], off
	s_waitcnt vmcnt(8)
	s_waitcnt lgkmcnt(0)
	s_barrier
; #define PG8_STAGE(bufoff, gbase, voff) do { _Pragma("unroll") for (int _i = 0; _i < 2; ++_i) \
;         __builtin_amdgcn_global_load_lds((const unsigned*)((const char*)(gbase) + (voff)[_i]), (PG8_LAS unsigned*)(lds + (bufoff) + ldsw + _i * 8192), 16, 0, 0); } while (0)
; #define PG8_LDA(dst, b, h) do { _Pragma("unroll") for (int m = 0; m < 4; ++m) _Pragma("unroll") for (int k = 0; k < 2; ++k) dst[m][k] = *(const PG8_LAS bf16x8*)(lds + PG8_SA(b, h) + aoff + m * 2048 + k * 1024); } while (0)
; #define PG8_LDB(dst, b, h) do { _Pragma("unroll") for (int n = 0; n < 2; ++n) _Pragma("unroll") for (int k = 0; k < 2; ++k) dst[n][k] = *(const PG8_LAS bf16x8*)(lds + PG8_SB(b, h) + boff + n * 2048 + k * 1024); } while (0)
; #define PG8_MMA(ai, bj, At, Bt) do { __builtin_amdgcn_s_setprio(1); _Pragma("unroll") for (int m = 0; m < 4; ++m) _Pragma("unroll") for (int n = 0; n < 2; ++n) _Pragma("unroll") for (int k = 0; k < 2; ++k) \
;         acc[ai][bj][m][n] = __builtin_amdgcn_mfma_f32_16x16x32_bf16(Bt[n][k], At[m][k], acc[ai][bj][m][n], 0, 0, 0); __builtin_amdgcn_s_setprio(0); } while (0)
; #define PG8_WAIT_V(n) asm volatile("s_waitcnt vmcnt(" #n ")" ::: "memory")
; #define PG8_WAIT_L(n) asm volatile("s_waitcnt lgkmcnt(" #n ")" ::: "memory")
; #define PG8_BAR __builtin_amdgcn_s_barrier()
; #define PG8_SCHED __builtin_amdgcn_sched_barrier(0)
; template <class Epi, class Sched, bool ALIGN_EPI = false, bool SP2 = false>
; __device__ __forceinline__ void gemm_phase(PG8_LAS unsigned char* lds, const Gemm g, const Sched& S, const Epi& E) {
;     ...
;             PG8_WAIT_V(8); PG8_WAIT_L(0); PG8_BAR; PG8_MMA(1, 0, At, B0); PG8_MMA(1, 1, At, B1); PG8_BAR; PG8_SCHED;
;             PG8_LDB(B0, 1, 0); PG8_LDB(B1, 1, 1); PG8_SCHED; PG8_LDA(At, 1, 0); PG8_STAGE(PG8_SA(0, 1), a2 + hstep, voffA);
;             PG8_WAIT_V(8); PG8_WAIT_L(0); PG8_BAR; PG8_MMA(0, 0, At, B0); PG8_MMA(0, 1, At, B1); PG8_BAR; PG8_SCHED;
	s_setprio 1
	s_waitcnt lgkmcnt(0)
	v_mfma_f32_16x16x32_bf16 v[60:63], v[64:67], v[160:163], v[60:63]
	v_mfma_f32_16x16x32_bf16 v[56:59], v[76:79], v[160:163], v[56:59]
	v_mfma_f32_16x16x32_bf16 v[44:47], v[64:67], v[168:171], v[44:47]
	v_mfma_f32_16x16x32_bf16 v[40:43], v[76:79], v[168:171], v[40:43]
	v_mfma_f32_16x16x32_bf16 v[28:31], v[64:67], v[176:179], v[28:31]
	v_mfma_f32_16x16x32_bf16 v[24:27], v[76:79], v[176:179], v[24:27]
	v_mfma_f32_16x16x32_bf16 v[12:15], v[64:67], v[184:187], v[12:15]
	v_mfma_f32_16x16x32_bf16 v[8:11], v[76:79], v[184:187], v[8:11]
	v_mfma_f32_16x16x32_bf16 v[60:63], v[68:71], v[164:167], v[60:63]
	v_mfma_f32_16x16x32_bf16 v[56:59], v[80:83], v[164:167], v[56:59]
	v_mfma_f32_16x16x32_bf16 v[44:47], v[68:71], v[172:175], v[44:47]
	v_mfma_f32_16x16x32_bf16 v[40:43], v[80:83], v[172:175], v[40:43]
	v_mfma_f32_16x16x32_bf16 v[28:31], v[68:71], v[180:183], v[28:31]
	v_mfma_f32_16x16x32_bf16 v[24:27], v[80:83], v[180:183], v[24:27]
	v_mfma_f32_16x16x32_bf16 v[12:15], v[68:71], v[188:191], v[12:15]
	v_mfma_f32_16x16x32_bf16 v[8:11], v[80:83], v[188:191], v[8:11]
	s_setprio 0
	s_setprio 1
	v_mfma_f32_16x16x32_bf16 v[52:55], v[144:147], v[160:163], v[52:55]
	v_mfma_f32_16x16x32_bf16 v[48:51], v[152:155], v[160:163], v[48:51]
	v_mfma_f32_16x16x32_bf16 v[36:39], v[144:147], v[168:171], v[36:39]
	v_mfma_f32_16x16x32_bf16 v[32:35], v[152:155], v[168:171], v[32:35]
	v_mfma_f32_16x16x32_bf16 v[20:23], v[144:147], v[176:179], v[20:23]
	v_mfma_f32_16x16x32_bf16 v[16:19], v[152:155], v[176:179], v[16:19]
	v_mfma_f32_16x16x32_bf16 v[4:7], v[144:147], v[184:187], v[4:7]
	v_mfma_f32_16x16x32_bf16 v[0:3], v[152:155], v[184:187], v[0:3]
	v_mfma_f32_16x16x32_bf16 v[52:55], v[148:151], v[164:167], v[52:55]
	v_mfma_f32_16x16x32_bf16 v[48:51], v[156:159], v[164:167], v[48:51]
	v_mfma_f32_16x16x32_bf16 v[36:39], v[148:151], v[172:175], v[36:39]
	v_mfma_f32_16x16x32_bf16 v[32:35], v[156:159], v[172:175], v[32:35]
	v_mfma_f32_16x16x32_bf16 v[20:23], v[148:151], v[180:183], v[20:23]
	v_mfma_f32_16x16x32_bf16 v[16:19], v[156:159], v[180:183], v[16:19]
	v_mfma_f32_16x16x32_bf16 v[4:7], v[148:151], v[188:191], v[4:7]
	v_mfma_f32_16x16x32_bf16 v[0:3], v[156:159], v[188:191], v[0:3]
	s_setprio 0
	s_barrier
	s_add_i32 s0, 0, 0x18000
	s_add_i32 s1, 0, 0x1c000
	v_add_u32_e32 v80, s0, v247
	v_add_u32_e32 v156, s1, v247
	ds_read_b128 v[64:67], v80
	ds_read_b128 v[68:71], v80 offset:1024
	ds_read_b128 v[76:79], v80 offset:2048
	ds_read_b128 v[80:83], v80 offset:3072
	ds_read_b128 v[144:147], v156
	ds_read_b128 v[148:151], v156 offset:1024
	ds_read_b128 v[152:155], v156 offset:2048
	ds_read_b128 v[156:159], v156 offset:3072
	s_add_u32 s58, s58, 0x40000
	s_addc_u32 s59, s59, 0
	s_mov_b32 m0, s60
	v_lshl_add_u64 v[200:201], s[58:59], 0, v[210:211]
	ds_read_b128 v[160:163], v251 offset:32768
	ds_read_b128 v[164:167], v251 offset:33792
	ds_read_b128 v[168:171], v251 offset:34816
	ds_read_b128 v[172:175], v251 offset:35840
	ds_read_b128 v[176:179], v251 offset:36864
	ds_read_b128 v[180:183], v251 offset:37888
	ds_read_b128 v[184:187], v251 offset:38912
	ds_read_b128 v[188:191], v251 offset:39936
	global_load_lds_dwordx4 v[200:201], off
	v_lshl_add_u64 v[200:201], s[58:59], 0, v[214:215]
	s_mov_b32 m0, s61
	s_nop 0
	global_load_lds_dwordx4 v[200:201], off
	s_waitcnt vmcnt(8)
	s_waitcnt lgkmcnt(0)
	s_barrier
	s_setprio 1
	s_waitcnt lgkmcnt(0)
	v_mfma_f32_16x16x32_bf16 v[140:143], v[64:67], v[160:163], v[140:143]
	v_mfma_f32_16x16x32_bf16 v[136:139], v[76:79], v[160:163], v[136:139]
	v_mfma_f32_16x16x32_bf16 v[124:127], v[64:67], v[168:171], v[124:127]
	v_mfma_f32_16x16x32_bf16 v[120:123], v[76:79], v[168:171], v[120:123]
	v_mfma_f32_16x16x32_bf16 v[108:111], v[64:67], v[176:179], v[108:111]
	v_mfma_f32_16x16x32_bf16 v[104:107], v[76:79], v[176:179], v[104:107]
	v_mfma_f32_16x16x32_bf16 v[92:95], v[64:67], v[184:187], v[92:95]
	v_mfma_f32_16x16x32_bf16 v[88:91], v[76:79], v[184:187], v[88:91]
	v_mfma_f32_16x16x32_bf16 v[140:143], v[68:71], v[164:167], v[140:143]
	v_mfma_f32_16x16x32_bf16 v[136:139], v[80:83], v[164:167], v[136:139]
	v_mfma_f32_16x16x32_bf16 v[124:127], v[68:71], v[172:175], v[124:127]
	v_mfma_f32_16x16x32_bf16 v[120:123], v[80:83], v[172:175], v[120:123]
	v_mfma_f32_16x16x32_bf16 v[108:111], v[68:71], v[180:183], v[108:111]
	v_mfma_f32_16x16x32_bf16 v[104:107], v[80:83], v[180:183], v[104:107]
	v_mfma_f32_16x16x32_bf16 v[92:95], v[68:71], v[188:191], v[92:95]
	v_mfma_f32_16x16x32_bf16 v[88:91], v[80:83], v[188:191], v[88:91]
	s_setprio 0
	s_setprio 1
	v_mfma_f32_16x16x32_bf16 v[132:135], v[144:147], v[160:163], v[132:135]
	v_mfma_f32_16x16x32_bf16 v[128:131], v[152:155], v[160:163], v[128:131]
	v_mfma_f32_16x16x32_bf16 v[116:119], v[144:147], v[168:171], v[116:119]
	v_mfma_f32_16x16x32_bf16 v[112:115], v[152:155], v[168:171], v[112:115]
	v_mfma_f32_16x16x32_bf16 v[100:103], v[144:147], v[176:179], v[100:103]
	v_mfma_f32_16x16x32_bf16 v[96:99], v[152:155], v[176:179], v[96:99]
	v_mfma_f32_16x16x32_bf16 v[84:87], v[144:147], v[184:187], v[84:87]
	v_mfma_f32_16x16x32_bf16 v[72:75], v[152:155], v[184:187], v[72:75]
	v_mfma_f32_16x16x32_bf16 v[132:135], v[148:151], v[164:167], v[132:135]
	v_mfma_f32_16x16x32_bf16 v[128:131], v[156:159], v[164:167], v[128:131]
	v_mfma_f32_16x16x32_bf16 v[116:119], v[148:151], v[172:175], v[116:119]
	v_mfma_f32_16x16x32_bf16 v[112:115], v[156:159], v[172:175], v[112:115]
	v_mfma_f32_16x16x32_bf16 v[100:103], v[148:151], v[180:183], v[100:103]
	v_mfma_f32_16x16x32_bf16 v[96:99], v[156:159], v[180:183], v[96:99]
	v_mfma_f32_16x16x32_bf16 v[84:87], v[148:151], v[188:191], v[84:87]
	v_mfma_f32_16x16x32_bf16 v[72:75], v[156:159], v[188:191], v[72:75]
	s_setprio 0
	s_barrier
; #define PG8_STAGE(bufoff, gbase, voff) do { _Pragma("unroll") for (int _i = 0; _i < 2; ++_i) \
;         __builtin_amdgcn_global_load_lds((const unsigned*)((const char*)(gbase) + (voff)[_i]), (PG8_LAS unsigned*)(lds + (bufoff) + ldsw + _i * 8192), 16, 0, 0); } while (0)
; #define PG8_LDA(dst, b, h) do { _Pragma("unroll") for (int m = 0; m < 4; ++m) _Pragma("unroll") for (int k = 0; k < 2; ++k) dst[m][k] = *(const PG8_LAS bf16x8*)(lds + PG8_SA(b, h) + aoff + m * 2048 + k * 1024); } while (0)
; #define PG8_MMA(ai, bj, At, Bt) do { __builtin_amdgcn_s_setprio(1); _Pragma("unroll") for (int m = 0; m < 4; ++m) _Pragma("unroll") for (int n = 0; n < 2; ++n) _Pragma("unroll") for (int k = 0; k < 2; ++k) \
;         acc[ai][bj][m][n] = __builtin_amdgcn_mfma_f32_16x16x32_bf16(Bt[n][k], At[m][k], acc[ai][bj][m][n], 0, 0, 0); __builtin_amdgcn_s_setprio(0); } while (0)
; #define PG8_WAIT_V(n) asm volatile("s_waitcnt vmcnt(" #n ")" ::: "memory")
; #define PG8_WAIT_L(n) asm volatile("s_waitcnt lgkmcnt(" #n ")" ::: "memory")
; #define PG8_BAR __builtin_amdgcn_s_barrier()
; #define PG8_SCHED __builtin_amdgcn_sched_barrier(0)
; template <class Epi, class Sched, bool ALIGN_EPI = false, bool SP2 = false>
; __device__ __forceinline__ void gemm_phase(PG8_LAS unsigned char* lds, const Gemm g, const Sched& S, const Epi& E) {
;     ...
;             PG8_LDA(At, 1, 1); PG8_STAGE(PG8_SB(1, 0), b3, voffB); PG8_STAGE(PG8_SB(1, 1), b3 + hstep, voffB); PG8_STAGE(PG8_SA(1, 0), a3, voffA);
;             PG8_WAIT_V(8); PG8_WAIT_L(0); PG8_BAR; PG8_MMA(1, 0, At, B0); PG8_MMA(1, 1, At, B1); PG8_BAR; PG8_SCHED;
;     ...
;         if constexpr (ALIGN_EPI) { if (wr == 0) PG8_BAR; }
	s_add_i32 s0, s0, s7
	v_lshl_add_u64 v[192:193], v[192:193], 0, s[42:43]
	s_mov_b32 m0, s0
	ds_read_b128 v[160:163], v251 offset:49152
	ds_read_b128 v[164:167], v251 offset:50176
	ds_read_b128 v[168:171], v251 offset:51200
	ds_read_b128 v[172:175], v251 offset:52224
	ds_read_b128 v[176:179], v251 offset:53248
	ds_read_b128 v[180:183], v251 offset:54272
	ds_read_b128 v[184:187], v251 offset:55296
	ds_read_b128 v[188:191], v251 offset:56320
	global_load_lds_dwordx4 v[192:193], off
	s_add_i32 m0, s0, 0x2000
	s_add_u32 s56, s56, 0x40080
	v_lshl_add_u64 v[192:193], v[194:195], 0, s[42:43]
	s_addc_u32 s57, s57, 0
	s_add_i32 s0, s1, s7
	global_load_lds_dwordx4 v[192:193], off
	v_lshl_add_u64 v[192:193], s[56:57], 0, v[212:213]
	s_mov_b32 m0, s0
	s_nop 0
	global_load_lds_dwordx4 v[192:193], off
	v_lshl_add_u64 v[192:193], s[56:57], 0, v[216:217]
	s_add_i32 m0, s0, 0x2000
	s_nop 0
	global_load_lds_dwordx4 v[192:193], off
	v_lshl_add_u64 v[192:193], v[196:197], 0, s[42:43]
	s_mov_b32 m0, s65
	s_nop 0
	global_load_lds_dwordx4 v[192:193], off
	v_lshl_add_u64 v[192:193], v[198:199], 0, s[42:43]
	s_mov_b32 m0, s66
	s_nop 0
	global_load_lds_dwordx4 v[192:193], off
	s_waitcnt vmcnt(8)
	s_waitcnt lgkmcnt(0)
	s_barrier
	s_setprio 1
	s_waitcnt lgkmcnt(0)
	v_mfma_f32_16x16x32_bf16 v[60:63], v[64:67], v[160:163], v[60:63]
	v_mfma_f32_16x16x32_bf16 v[56:59], v[76:79], v[160:163], v[56:59]
	v_mfma_f32_16x16x32_bf16 v[44:47], v[64:67], v[168:171], v[44:47]
	v_mfma_f32_16x16x32_bf16 v[40:43], v[76:79], v[168:171], v[40:43]
	v_mfma_f32_16x16x32_bf16 v[28:31], v[64:67], v[176:179], v[28:31]
	v_mfma_f32_16x16x32_bf16 v[24:27], v[76:79], v[176:179], v[24:27]
	v_mfma_f32_16x16x32_bf16 v[12:15], v[64:67], v[184:187], v[12:15]
	v_mfma_f32_16x16x32_bf16 v[8:11], v[76:79], v[184:187], v[8:11]
	v_mfma_f32_16x16x32_bf16 v[60:63], v[68:71], v[164:167], v[60:63]
	v_mfma_f32_16x16x32_bf16 v[56:59], v[80:83], v[164:167], v[56:59]
	v_mfma_f32_16x16x32_bf16 v[44:47], v[68:71], v[172:175], v[44:47]
	v_mfma_f32_16x16x32_bf16 v[40:43], v[80:83], v[172:175], v[40:43]
	v_mfma_f32_16x16x32_bf16 v[28:31], v[68:71], v[180:183], v[28:31]
	v_mfma_f32_16x16x32_bf16 v[24:27], v[80:83], v[180:183], v[24:27]
	v_mfma_f32_16x16x32_bf16 v[12:15], v[68:71], v[188:191], v[12:15]
	v_mfma_f32_16x16x32_bf16 v[8:11], v[80:83], v[188:191], v[8:11]
	s_setprio 0
	s_setprio 1
	v_mfma_f32_16x16x32_bf16 v[52:55], v[144:147], v[160:163], v[52:55]
	v_mfma_f32_16x16x32_bf16 v[48:51], v[152:155], v[160:163], v[48:51]
	v_mfma_f32_16x16x32_bf16 v[36:39], v[144:147], v[168:171], v[36:39]
	v_mfma_f32_16x16x32_bf16 v[32:35], v[152:155], v[168:171], v[32:35]
	v_mfma_f32_16x16x32_bf16 v[20:23], v[144:147], v[176:179], v[20:23]
	v_mfma_f32_16x16x32_bf16 v[16:19], v[152:155], v[176:179], v[16:19]
	v_mfma_f32_16x16x32_bf16 v[4:7], v[144:147], v[184:187], v[4:7]
	v_mfma_f32_16x16x32_bf16 v[0:3], v[152:155], v[184:187], v[0:3]
	v_mfma_f32_16x16x32_bf16 v[52:55], v[148:151], v[164:167], v[52:55]
	v_mfma_f32_16x16x32_bf16 v[48:51], v[156:159], v[164:167], v[48:51]
	v_mfma_f32_16x16x32_bf16 v[36:39], v[148:151], v[172:175], v[36:39]
	v_mfma_f32_16x16x32_bf16 v[32:35], v[156:159], v[172:175], v[32:35]
	v_mfma_f32_16x16x32_bf16 v[20:23], v[148:151], v[180:183], v[20:23]
	v_mfma_f32_16x16x32_bf16 v[16:19], v[156:159], v[180:183], v[16:19]
	v_mfma_f32_16x16x32_bf16 v[4:7], v[148:151], v[188:191], v[4:7]
	v_mfma_f32_16x16x32_bf16 v[0:3], v[156:159], v[188:191], v[0:3]
	s_setprio 0
	s_add_i32 s77, s77, 2
	s_add_u32 s54, s54, 0x100
	s_addc_u32 s55, s55, 0
	s_add_u32 s75, s75, 0x100
	s_addc_u32 s76, s76, 0
	s_cmp_gt_u32 s77, 13
	s_cbranch_scc0 .Lkrot2
	s_barrier
	s_and_b64 vcc, exec, s[44:45]
	s_cbranch_vccz .LBB0_461
	s_barrier

;     __device__ __forceinline__ long a_off(int pm, size_t tstep) const { return (long)pm * (long)tstep; }
; template <class Epi, class Sched, bool ALIGN_EPI = false, bool SP2 = false>
; __device__ __forceinline__ void gemm_phase(PG8_LAS unsigned char* lds, const Gemm g, const Sched& S, const Epi& E) {
;     ...
;         const bool has_next = S.next(ui + 1, nxt);
;         const char* nA = has_next ? (const char*)g.A + S.a_off(nxt.pm, tstep) : cA; const char* nB = has_next ? (const char*)g.Bt + (size_t)nxt.pn * tstep : cB;
;         for (int t = 0; t < nt; t += 2) {
;             const bool last = (t == nt - 2);
;             const char* a1 = cA + (size_t)(t + 1) * kstep;
;             const char* a2 = last ? nA : cA + (size_t)(t + 2) * kstep; const char* b2 = last ? nB : cB + (size_t)(t + 2) * kstep;
;     ...
;         for (int a = 0; a < 2; ++a)
; #pragma unroll
;             for (int b = 0; b < 2; ++b)
; #pragma unroll
;                 for (int m = 0; m < 4; ++m)
; #pragma unroll
;                     for (int n = 0; n < 2; ++n) acc[a][b][m][n] = (f32x4){0.f, 0.f, 0.f, 0.f};
.LBB0_573:
	s_ashr_i32 s63, s62, 31
	s_lshl_b64 s[16:17], s[62:63], 19
	s_add_u32 s66, s59, s16
	s_addc_u32 s67, s73, s17
	s_and_b64 s[10:11], s[10:11], exec
	s_cselect_b32 s16, s67, s13
	s_cselect_b32 s17, s66, s12
	s_add_u32 s10, s14, 0x40080
	s_addc_u32 s11, s15, 0
	s_add_u32 s19, s12, 0x100
	v_mov_b32_e32 v96, 0
	s_addc_u32 s20, s13, 0
	s_mov_b32 s21, -2
	v_mov_b32_e32 v97, v96
	v_mov_b32_e32 v98, v96
	v_mov_b32_e32 v99, v96
	v_mov_b32_e32 v100, v96
	v_mov_b32_e32 v101, v96
	v_mov_b32_e32 v102, v96
	v_mov_b32_e32 v103, v96
	v_mov_b32_e32 v0, v96
	v_mov_b32_e32 v1, v96
	v_mov_b32_e32 v2, v96
	v_mov_b32_e32 v3, v96
	v_mov_b32_e32 v48, v96
	v_mov_b32_e32 v49, v96
	v_mov_b32_e32 v50, v96
	v_mov_b32_e32 v51, v96
	v_mov_b32_e32 v8, v96
	v_mov_b32_e32 v9, v96
	v_mov_b32_e32 v10, v96
	v_mov_b32_e32 v11, v96
	v_mov_b32_e32 v56, v96
	v_mov_b32_e32 v57, v96
	v_mov_b32_e32 v58, v96
	v_mov_b32_e32 v59, v96
	v_mov_b32_e32 v16, v96
	v_mov_b32_e32 v17, v96
	v_mov_b32_e32 v18, v96
	v_mov_b32_e32 v19, v96
	v_mov_b32_e32 v64, v96
	v_mov_b32_e32 v65, v96
	v_mov_b32_e32 v66, v96
	v_mov_b32_e32 v67, v96
	v_mov_b32_e32 v104, v96
	v_mov_b32_e32 v105, v96
	v_mov_b32_e32 v106, v96
	v_mov_b32_e32 v107, v96
	v_mov_b32_e32 v108, v96
	v_mov_b32_e32 v109, v96
	v_mov_b32_e32 v110, v96
	v_mov_b32_e32 v111, v96
	v_mov_b32_e32 v4, v96
	v_mov_b32_e32 v5, v96
	v_mov_b32_e32 v6, v96
	v_mov_b32_e32 v7, v96
	v_mov_b32_e32 v52, v96
	v_mov_b32_e32 v53, v96
	v_mov_b32_e32 v54, v96
	v_mov_b32_e32 v55, v96
	v_mov_b32_e32 v12, v96
	v_mov_b32_e32 v13, v96
	v_mov_b32_e32 v14, v96
	v_mov_b32_e32 v15, v96
	v_mov_b32_e32 v60, v96
	v_mov_b32_e32 v61, v96
	v_mov_b32_e32 v62, v96
	v_mov_b32_e32 v63, v96
	v_mov_b32_e32 v20, v96
	v_mov_b32_e32 v21, v96
	v_mov_b32_e32 v22, v96
	v_mov_b32_e32 v23, v96
	v_mov_b32_e32 v68, v96
	v_mov_b32_e32 v69, v96
	v_mov_b32_e32 v70, v96
	v_mov_b32_e32 v71, v96
	v_mov_b32_e32 v112, v96
	v_mov_b32_e32 v113, v96
	v_mov_b32_e32 v114, v96
	v_mov_b32_e32 v115, v96
	v_mov_b32_e32 v116, v96
	v_mov_b32_e32 v117, v96
	v_mov_b32_e32 v118, v96
	v_mov_b32_e32 v119, v96
	v_mov_b32_e32 v24, v96
	v_mov_b32_e32 v25, v96
	v_mov_b32_e32 v26, v96
	v_mov_b32_e32 v27, v96
	v_mov_b32_e32 v72, v96
	v_mov_b32_e32 v73, v96
	v_mov_b32_e32 v74, v96
	v_mov_b32_e32 v75, v96
	v_mov_b32_e32 v32, v96
	v_mov_b32_e32 v33, v96
	v_mov_b32_e32 v34, v96
	v_mov_b32_e32 v35, v96
	v_mov_b32_e32 v80, v96
	v_mov_b32_e32 v81, v96
	v_mov_b32_e32 v82, v96
	v_mov_b32_e32 v83, v96
	v_mov_b32_e32 v40, v96
	v_mov_b32_e32 v41, v96
	v_mov_b32_e32 v42, v96
	v_mov_b32_e32 v43, v96
	v_mov_b32_e32 v88, v96
	v_mov_b32_e32 v89, v96
	v_mov_b32_e32 v90, v96
	v_mov_b32_e32 v91, v96
	v_mov_b32_e32 v120, v96
	v_mov_b32_e32 v121, v96
	v_mov_b32_e32 v122, v96
	v_mov_b32_e32 v123, v96
	v_mov_b32_e32 v124, v96
	v_mov_b32_e32 v125, v96
	v_mov_b32_e32 v126, v96
	v_mov_b32_e32 v127, v96
	v_mov_b32_e32 v28, v96
	v_mov_b32_e32 v29, v96
	v_mov_b32_e32 v30, v96
	v_mov_b32_e32 v31, v96
	v_mov_b32_e32 v76, v96
	v_mov_b32_e32 v77, v96
	v_mov_b32_e32 v78, v96
	v_mov_b32_e32 v79, v96
	v_mov_b32_e32 v36, v96
	v_mov_b32_e32 v37, v96
	v_mov_b32_e32 v38, v96
	v_mov_b32_e32 v39, v96
	v_mov_b32_e32 v84, v96
	v_mov_b32_e32 v85, v96
	v_mov_b32_e32 v86, v96
	v_mov_b32_e32 v87, v96
	v_mov_b32_e32 v44, v96
	v_mov_b32_e32 v45, v96
	v_mov_b32_e32 v46, v96
	v_mov_b32_e32 v47, v96
	v_mov_b32_e32 v92, v96
	v_mov_b32_e32 v93, v96
	v_mov_b32_e32 v94, v96
	v_mov_b32_e32 v95, v96
	s_branch .LBB0_574

; #define PG8_STAGE(bufoff, gbase, voff) do { _Pragma("unroll") for (int _i = 0; _i < 2; ++_i) \
;         __builtin_amdgcn_global_load_lds((const unsigned*)((const char*)(gbase) + (voff)[_i]), (PG8_LAS unsigned*)(lds + (bufoff) + ldsw + _i * 8192), 16, 0, 0); } while (0)
; #define PG8_LDA(dst, b, h) do { _Pragma("unroll") for (int m = 0; m < 4; ++m) _Pragma("unroll") for (int k = 0; k < 2; ++k) dst[m][k] = *(const PG8_LAS bf16x8*)(lds + PG8_SA(b, h) + aoff + m * 2048 + k * 1024); } while (0)
; #define PG8_LDB(dst, b, h) do { _Pragma("unroll") for (int n = 0; n < 2; ++n) _Pragma("unroll") for (int k = 0; k < 2; ++k) dst[n][k] = *(const PG8_LAS bf16x8*)(lds + PG8_SB(b, h) + boff + n * 2048 + k * 1024); } while (0)
; #define PG8_MMA(ai, bj, At, Bt) do { __builtin_amdgcn_s_setprio(1); _Pragma("unroll") for (int m = 0; m < 4; ++m) _Pragma("unroll") for (int n = 0; n < 2; ++n) _Pragma("unroll") for (int k = 0; k < 2; ++k) \
;         acc[ai][bj][m][n] = __builtin_amdgcn_mfma_f32_16x16x32_bf16(Bt[n][k], At[m][k], acc[ai][bj][m][n], 0, 0, 0); __builtin_amdgcn_s_setprio(0); } while (0)
; #define PG8_WAIT_V(n) asm volatile("s_waitcnt vmcnt(" #n ")" ::: "memory")
; #define PG8_WAIT_L(n) asm volatile("s_waitcnt lgkmcnt(" #n ")" ::: "memory")
; #define PG8_BAR __builtin_amdgcn_s_barrier()
; #define PG8_SCHED __builtin_amdgcn_sched_barrier(0)
; template <class Epi, class Sched, bool ALIGN_EPI = false, bool SP2 = false>
; __device__ __forceinline__ void gemm_phase(PG8_LAS unsigned char* lds, const Gemm g, const Sched& S, const Epi& E) {
;     ...
;             PG8_LDB(B0, 0, 0); PG8_LDB(B1, 0, 1); PG8_SCHED; PG8_LDA(At, 0, 0); PG8_STAGE(PG8_SA(1, 1), a1 + hstep, voffA);
;             PG8_WAIT_V(8); PG8_WAIT_L(0); PG8_BAR; PG8_MMA(0, 0, At, B0); PG8_MMA(0, 1, At, B1); PG8_BAR; PG8_SCHED;
;             PG8_LDA(At, 0, 1); PG8_STAGE(PG8_SB(0, 0), b2, voffB); PG8_STAGE(PG8_SB(0, 1), b2 + hstep, voffB); PG8_STAGE(PG8_SA(0, 0), a2, voffA);
;             PG8_WAIT_V(8); PG8_WAIT_L(0); PG8_BAR; PG8_MMA(1, 0, At, B0); PG8_MMA(1, 1, At, B1); PG8_BAR; PG8_SCHED;
.LBB0_574:
	ds_read_b128 v[128:131], v224
	ds_read_b128 v[132:135], v224 offset:1024
	ds_read_b128 v[136:139], v224 offset:2048
	ds_read_b128 v[140:143], v224 offset:3072
	ds_read_b128 v[144:147], v225
	ds_read_b128 v[148:151], v225 offset:1024
	ds_read_b128 v[152:155], v225 offset:2048
	ds_read_b128 v[156:159], v225 offset:3072
	s_add_u32 s0, s10, 0xfffc0080
	s_addc_u32 s1, s11, -1
	s_cmp_eq_u32 s21, 12
	s_cselect_b32 s15, s65, s1
	s_cselect_b32 s14, s64, s0
	s_cselect_b32 s13, s16, s20
	s_cselect_b32 s12, s17, s19
	v_lshl_add_u64 v[214:215], s[10:11], 0, v[186:187]
	s_add_i32 m0, s69, 0xc000
	ds_read_b128 v[160:163], v226
	ds_read_b128 v[164:167], v226 offset:1024
	ds_read_b128 v[168:171], v226 offset:2048
	ds_read_b128 v[172:175], v226 offset:3072
	ds_read_b128 v[196:199], v226 offset:4096
	ds_read_b128 v[200:203], v226 offset:5120
	ds_read_b128 v[204:207], v226 offset:6144
	ds_read_b128 v[210:213], v226 offset:7168
	global_load_lds_dwordx4 v[214:215], off
	v_lshl_add_u64 v[214:215], s[10:11], 0, v[188:189]
	s_add_i32 m0, s69, 0xe000
	s_nop 0
	global_load_lds_dwordx4 v[214:215], off
	s_waitcnt vmcnt(8)
	s_waitcnt lgkmcnt(0)
	s_barrier
	s_setprio 1
	s_waitcnt lgkmcnt(0)
	v_mfma_f32_16x16x32_bf16 v[92:95], v[128:131], v[160:163], v[92:95]
	v_mfma_f32_16x16x32_bf16 v[44:47], v[136:139], v[160:163], v[44:47]
	v_mfma_f32_16x16x32_bf16 v[84:87], v[128:131], v[168:171], v[84:87]
	v_mfma_f32_16x16x32_bf16 v[36:39], v[136:139], v[168:171], v[36:39]
	v_mfma_f32_16x16x32_bf16 v[76:79], v[128:131], v[196:199], v[76:79]
	v_mfma_f32_16x16x32_bf16 v[28:31], v[136:139], v[196:199], v[28:31]
	v_mfma_f32_16x16x32_bf16 v[124:127], v[128:131], v[204:207], v[124:127]
	v_mfma_f32_16x16x32_bf16 v[120:123], v[136:139], v[204:207], v[120:123]
	v_mfma_f32_16x16x32_bf16 v[92:95], v[132:135], v[164:167], v[92:95]
	v_mfma_f32_16x16x32_bf16 v[44:47], v[140:143], v[164:167], v[44:47]
	v_mfma_f32_16x16x32_bf16 v[84:87], v[132:135], v[172:175], v[84:87]
	v_mfma_f32_16x16x32_bf16 v[36:39], v[140:143], v[172:175], v[36:39]
	v_mfma_f32_16x16x32_bf16 v[76:79], v[132:135], v[200:203], v[76:79]
	v_mfma_f32_16x16x32_bf16 v[28:31], v[140:143], v[200:203], v[28:31]
	v_mfma_f32_16x16x32_bf16 v[124:127], v[132:135], v[210:213], v[124:127]
	v_mfma_f32_16x16x32_bf16 v[120:123], v[140:143], v[210:213], v[120:123]
	s_setprio 0
	s_setprio 1
	v_mfma_f32_16x16x32_bf16 v[88:91], v[144:147], v[160:163], v[88:91]
	v_mfma_f32_16x16x32_bf16 v[40:43], v[152:155], v[160:163], v[40:43]
	v_mfma_f32_16x16x32_bf16 v[80:83], v[144:147], v[168:171], v[80:83]
	v_mfma_f32_16x16x32_bf16 v[32:35], v[152:155], v[168:171], v[32:35]
	v_mfma_f32_16x16x32_bf16 v[72:75], v[144:147], v[196:199], v[72:75]
	v_mfma_f32_16x16x32_bf16 v[24:27], v[152:155], v[196:199], v[24:27]
	v_mfma_f32_16x16x32_bf16 v[116:119], v[144:147], v[204:207], v[116:119]
	v_mfma_f32_16x16x32_bf16 v[112:115], v[152:155], v[204:207], v[112:115]
	v_mfma_f32_16x16x32_bf16 v[88:91], v[148:151], v[164:167], v[88:91]
	v_mfma_f32_16x16x32_bf16 v[40:43], v[156:159], v[164:167], v[40:43]
	v_mfma_f32_16x16x32_bf16 v[80:83], v[148:151], v[172:175], v[80:83]
	v_mfma_f32_16x16x32_bf16 v[32:35], v[156:159], v[172:175], v[32:35]
	v_mfma_f32_16x16x32_bf16 v[72:75], v[148:151], v[200:203], v[72:75]
	v_mfma_f32_16x16x32_bf16 v[24:27], v[156:159], v[200:203], v[24:27]
	v_mfma_f32_16x16x32_bf16 v[116:119], v[148:151], v[210:213], v[116:119]
	v_mfma_f32_16x16x32_bf16 v[112:115], v[156:159], v[210:213], v[112:115]
	s_setprio 0
	s_barrier
	s_add_i32 s0, s97, s75
	v_lshl_add_u64 v[214:215], s[12:13], 0, v[178:179]
	s_mov_b32 m0, s0
	ds_read_b128 v[160:163], v226 offset:16384
	ds_read_b128 v[164:167], v226 offset:17408
	ds_read_b128 v[168:171], v226 offset:18432
	ds_read_b128 v[172:175], v226 offset:19456
	ds_read_b128 v[196:199], v226 offset:20480
	ds_read_b128 v[200:203], v226 offset:21504
	ds_read_b128 v[204:207], v226 offset:22528
	ds_read_b128 v[210:213], v226 offset:23552
	global_load_lds_dwordx4 v[214:215], off
	s_add_i32 m0, s0, 0x2000
	s_add_u32 s22, s12, 0x40000
	v_lshl_add_u64 v[216:217], s[12:13], 0, v[182:183]
	s_addc_u32 s23, s13, 0
	s_add_i32 s0, s72, s75
	global_load_lds_dwordx4 v[216:217], off
	v_lshl_add_u64 v[218:219], s[22:23], 0, v[178:179]
	s_mov_b32 m0, s0
	v_lshl_add_u64 v[220:221], s[14:15], 0, v[180:181]
	global_load_lds_dwordx4 v[218:219], off
	v_lshl_add_u64 v[218:219], s[22:23], 0, v[182:183]
	s_add_i32 m0, s0, 0x2000
	s_nop 0
	global_load_lds_dwordx4 v[218:219], off
	v_lshl_add_u64 v[218:219], s[14:15], 0, v[176:177]
	s_mov_b32 m0, s69
	s_nop 0
	global_load_lds_dwordx4 v[218:219], off
	s_mov_b32 m0, s76
	s_nop 0
	global_load_lds_dwordx4 v[220:221], off
	s_waitcnt vmcnt(8)
	s_waitcnt lgkmcnt(0)
	s_barrier
; #define PG8_STAGE(bufoff, gbase, voff) do { _Pragma("unroll") for (int _i = 0; _i < 2; ++_i) \
;         __builtin_amdgcn_global_load_lds((const unsigned*)((const char*)(gbase) + (voff)[_i]), (PG8_LAS unsigned*)(lds + (bufoff) + ldsw + _i * 8192), 16, 0, 0); } while (0)
; #define PG8_LDA(dst, b, h) do { _Pragma("unroll") for (int m = 0; m < 4; ++m) _Pragma("unroll") for (int k = 0; k < 2; ++k) dst[m][k] = *(const PG8_LAS bf16x8*)(lds + PG8_SA(b, h) + aoff + m * 2048 + k * 1024); } while (0)
; #define PG8_LDB(dst, b, h) do { _Pragma("unroll") for (int n = 0; n < 2; ++n) _Pragma("unroll") for (int k = 0; k < 2; ++k) dst[n][k] = *(const PG8_LAS bf16x8*)(lds + PG8_SB(b, h) + boff + n * 2048 + k * 1024); } while (0)
; #define PG8_MMA(ai, bj, At, Bt) do { __builtin_amdgcn_s_setprio(1); _Pragma("unroll") for (int m = 0; m < 4; ++m) _Pragma("unroll") for (int n = 0; n < 2; ++n) _Pragma("unroll") for (int k = 0; k < 2; ++k) \
;         acc[ai][bj][m][n] = __builtin_amdgcn_mfma_f32_16x16x32_bf16(Bt[n][k], At[m][k], acc[ai][bj][m][n], 0, 0, 0); __builtin_amdgcn_s_setprio(0); } while (0)
; #define PG8_WAIT_V(n) asm volatile("s_waitcnt vmcnt(" #n ")" ::: "memory")
; #define PG8_WAIT_L(n) asm volatile("s_waitcnt lgkmcnt(" #n ")" ::: "memory")
; #define PG8_BAR __builtin_amdgcn_s_barrier()
; #define PG8_SCHED __builtin_amdgcn_sched_barrier(0)
; template <class Epi, class Sched, bool ALIGN_EPI = false, bool SP2 = false>
; __device__ __forceinline__ void gemm_phase(PG8_LAS unsigned char* lds, const Gemm g, const Sched& S, const Epi& E) {
;     ...
;             PG8_WAIT_V(8); PG8_WAIT_L(0); PG8_BAR; PG8_MMA(1, 0, At, B0); PG8_MMA(1, 1, At, B1); PG8_BAR; PG8_SCHED;
;             PG8_LDB(B0, 1, 0); PG8_LDB(B1, 1, 1); PG8_SCHED; PG8_LDA(At, 1, 0); PG8_STAGE(PG8_SA(0, 1), a2 + hstep, voffA);
;             PG8_WAIT_V(8); PG8_WAIT_L(0); PG8_BAR; PG8_MMA(0, 0, At, B0); PG8_MMA(0, 1, At, B1); PG8_BAR; PG8_SCHED;
	s_setprio 1
	s_waitcnt lgkmcnt(0)
	v_mfma_f32_16x16x32_bf16 v[68:71], v[128:131], v[160:163], v[68:71]
	v_mfma_f32_16x16x32_bf16 v[20:23], v[136:139], v[160:163], v[20:23]
	v_mfma_f32_16x16x32_bf16 v[60:63], v[128:131], v[168:171], v[60:63]
	v_mfma_f32_16x16x32_bf16 v[12:15], v[136:139], v[168:171], v[12:15]
	v_mfma_f32_16x16x32_bf16 v[52:55], v[128:131], v[196:199], v[52:55]
	v_mfma_f32_16x16x32_bf16 v[4:7], v[136:139], v[196:199], v[4:7]
	v_mfma_f32_16x16x32_bf16 v[108:111], v[128:131], v[204:207], v[108:111]
	v_mfma_f32_16x16x32_bf16 v[104:107], v[136:139], v[204:207], v[104:107]
	v_mfma_f32_16x16x32_bf16 v[68:71], v[132:135], v[164:167], v[68:71]
	v_mfma_f32_16x16x32_bf16 v[20:23], v[140:143], v[164:167], v[20:23]
	v_mfma_f32_16x16x32_bf16 v[60:63], v[132:135], v[172:175], v[60:63]
	v_mfma_f32_16x16x32_bf16 v[12:15], v[140:143], v[172:175], v[12:15]
	v_mfma_f32_16x16x32_bf16 v[52:55], v[132:135], v[200:203], v[52:55]
	v_mfma_f32_16x16x32_bf16 v[4:7], v[140:143], v[200:203], v[4:7]
	v_mfma_f32_16x16x32_bf16 v[108:111], v[132:135], v[210:213], v[108:111]
	v_mfma_f32_16x16x32_bf16 v[104:107], v[140:143], v[210:213], v[104:107]
	s_setprio 0
	s_setprio 1
	v_mfma_f32_16x16x32_bf16 v[64:67], v[144:147], v[160:163], v[64:67]
	v_mfma_f32_16x16x32_bf16 v[16:19], v[152:155], v[160:163], v[16:19]
	v_mfma_f32_16x16x32_bf16 v[56:59], v[144:147], v[168:171], v[56:59]
	v_mfma_f32_16x16x32_bf16 v[8:11], v[152:155], v[168:171], v[8:11]
	v_mfma_f32_16x16x32_bf16 v[48:51], v[144:147], v[196:199], v[48:51]
	v_mfma_f32_16x16x32_bf16 v[0:3], v[152:155], v[196:199], v[0:3]
	v_mfma_f32_16x16x32_bf16 v[100:103], v[144:147], v[204:207], v[100:103]
	v_mfma_f32_16x16x32_bf16 v[96:99], v[152:155], v[204:207], v[96:99]
	v_mfma_f32_16x16x32_bf16 v[64:67], v[148:151], v[164:167], v[64:67]
	v_mfma_f32_16x16x32_bf16 v[16:19], v[156:159], v[164:167], v[16:19]
	v_mfma_f32_16x16x32_bf16 v[56:59], v[148:151], v[172:175], v[56:59]
	v_mfma_f32_16x16x32_bf16 v[8:11], v[156:159], v[172:175], v[8:11]
	v_mfma_f32_16x16x32_bf16 v[48:51], v[148:151], v[200:203], v[48:51]
	v_mfma_f32_16x16x32_bf16 v[0:3], v[156:159], v[200:203], v[0:3]
	v_mfma_f32_16x16x32_bf16 v[100:103], v[148:151], v[210:213], v[100:103]
	v_mfma_f32_16x16x32_bf16 v[96:99], v[156:159], v[210:213], v[96:99]
	s_setprio 0
	s_barrier
	s_add_i32 s0, 0, 0x18000
	s_add_i32 s1, 0, 0x1c000
	v_add_u32_e32 v140, s0, v223
	v_add_u32_e32 v156, s1, v223
	ds_read_b128 v[128:131], v140
	ds_read_b128 v[132:135], v140 offset:1024
	ds_read_b128 v[136:139], v140 offset:2048
	ds_read_b128 v[140:143], v140 offset:3072
	ds_read_b128 v[144:147], v156
	ds_read_b128 v[148:151], v156 offset:1024
	ds_read_b128 v[152:155], v156 offset:2048
	ds_read_b128 v[156:159], v156 offset:3072
	s_add_u32 s14, s14, 0x40000
	s_addc_u32 s15, s15, 0
	s_mov_b32 m0, s77
	v_lshl_add_u64 v[228:229], s[14:15], 0, v[176:177]
	ds_read_b128 v[160:163], v226 offset:32768
	ds_read_b128 v[164:167], v226 offset:33792
	ds_read_b128 v[168:171], v226 offset:34816
	ds_read_b128 v[172:175], v226 offset:35840
	ds_read_b128 v[196:199], v226 offset:36864
	ds_read_b128 v[200:203], v226 offset:37888
	ds_read_b128 v[204:207], v226 offset:38912
	ds_read_b128 v[210:213], v226 offset:39936
	global_load_lds_dwordx4 v[228:229], off
	v_lshl_add_u64 v[228:229], s[14:15], 0, v[180:181]
	s_mov_b32 m0, s78
	s_nop 0
	global_load_lds_dwordx4 v[228:229], off
	s_waitcnt vmcnt(8)
	s_waitcnt lgkmcnt(0)
	s_barrier
	s_setprio 1
	s_waitcnt lgkmcnt(0)
	v_mfma_f32_16x16x32_bf16 v[92:95], v[128:131], v[160:163], v[92:95]
	v_mfma_f32_16x16x32_bf16 v[44:47], v[136:139], v[160:163], v[44:47]
	v_mfma_f32_16x16x32_bf16 v[84:87], v[128:131], v[168:171], v[84:87]
	v_mfma_f32_16x16x32_bf16 v[36:39], v[136:139], v[168:171], v[36:39]
	v_mfma_f32_16x16x32_bf16 v[76:79], v[128:131], v[196:199], v[76:79]
	v_mfma_f32_16x16x32_bf16 v[28:31], v[136:139], v[196:199], v[28:31]
	v_mfma_f32_16x16x32_bf16 v[124:127], v[128:131], v[204:207], v[124:127]
	v_mfma_f32_16x16x32_bf16 v[120:123], v[136:139], v[204:207], v[120:123]
	v_mfma_f32_16x16x32_bf16 v[92:95], v[132:135], v[164:167], v[92:95]
	v_mfma_f32_16x16x32_bf16 v[44:47], v[140:143], v[164:167], v[44:47]
	v_mfma_f32_16x16x32_bf16 v[84:87], v[132:135], v[172:175], v[84:87]
	v_mfma_f32_16x16x32_bf16 v[36:39], v[140:143], v[172:175], v[36:39]
	v_mfma_f32_16x16x32_bf16 v[76:79], v[132:135], v[200:203], v[76:79]
	v_mfma_f32_16x16x32_bf16 v[28:31], v[140:143], v[200:203], v[28:31]
	v_mfma_f32_16x16x32_bf16 v[124:127], v[132:135], v[210:213], v[124:127]
	v_mfma_f32_16x16x32_bf16 v[120:123], v[140:143], v[210:213], v[120:123]
	s_setprio 0
	s_setprio 1
	v_mfma_f32_16x16x32_bf16 v[88:91], v[144:147], v[160:163], v[88:91]
	v_mfma_f32_16x16x32_bf16 v[40:43], v[152:155], v[160:163], v[40:43]
	v_mfma_f32_16x16x32_bf16 v[80:83], v[144:147], v[168:171], v[80:83]
	v_mfma_f32_16x16x32_bf16 v[32:35], v[152:155], v[168:171], v[32:35]
	v_mfma_f32_16x16x32_bf16 v[72:75], v[144:147], v[196:199], v[72:75]
	v_mfma_f32_16x16x32_bf16 v[24:27], v[152:155], v[196:199], v[24:27]
	v_mfma_f32_16x16x32_bf16 v[116:119], v[144:147], v[204:207], v[116:119]
	v_mfma_f32_16x16x32_bf16 v[112:115], v[152:155], v[204:207], v[112:115]
	v_mfma_f32_16x16x32_bf16 v[88:91], v[148:151], v[164:167], v[88:91]
	v_mfma_f32_16x16x32_bf16 v[40:43], v[156:159], v[164:167], v[40:43]
	v_mfma_f32_16x16x32_bf16 v[80:83], v[148:151], v[172:175], v[80:83]
	v_mfma_f32_16x16x32_bf16 v[32:35], v[156:159], v[172:175], v[32:35]
	v_mfma_f32_16x16x32_bf16 v[72:75], v[148:151], v[200:203], v[72:75]
	v_mfma_f32_16x16x32_bf16 v[24:27], v[156:159], v[200:203], v[24:27]
	v_mfma_f32_16x16x32_bf16 v[116:119], v[148:151], v[210:213], v[116:119]
	v_mfma_f32_16x16x32_bf16 v[112:115], v[156:159], v[210:213], v[112:115]
	s_setprio 0
	s_barrier
; #define PG8_STAGE(bufoff, gbase, voff) do { _Pragma("unroll") for (int _i = 0; _i < 2; ++_i) \
;         __builtin_amdgcn_global_load_lds((const unsigned*)((const char*)(gbase) + (voff)[_i]), (PG8_LAS unsigned*)(lds + (bufoff) + ldsw + _i * 8192), 16, 0, 0); } while (0)
; #define PG8_LDA(dst, b, h) do { _Pragma("unroll") for (int m = 0; m < 4; ++m) _Pragma("unroll") for (int k = 0; k < 2; ++k) dst[m][k] = *(const PG8_LAS bf16x8*)(lds + PG8_SA(b, h) + aoff + m * 2048 + k * 1024); } while (0)
; #define PG8_MMA(ai, bj, At, Bt) do { __builtin_amdgcn_s_setprio(1); _Pragma("unroll") for (int m = 0; m < 4; ++m) _Pragma("unroll") for (int n = 0; n < 2; ++n) _Pragma("unroll") for (int k = 0; k < 2; ++k) \
;         acc[ai][bj][m][n] = __builtin_amdgcn_mfma_f32_16x16x32_bf16(Bt[n][k], At[m][k], acc[ai][bj][m][n], 0, 0, 0); __builtin_amdgcn_s_setprio(0); } while (0)
; #define PG8_WAIT_V(n) asm volatile("s_waitcnt vmcnt(" #n ")" ::: "memory")
; #define PG8_WAIT_L(n) asm volatile("s_waitcnt lgkmcnt(" #n ")" ::: "memory")
; #define PG8_BAR __builtin_amdgcn_s_barrier()
; #define PG8_SCHED __builtin_amdgcn_sched_barrier(0)
; template <class Epi, class Sched, bool ALIGN_EPI = false, bool SP2 = false>
; __device__ __forceinline__ void gemm_phase(PG8_LAS unsigned char* lds, const Gemm g, const Sched& S, const Epi& E) {
;     ...
;         for (int t = 0; t < nt; t += 2) {
;     ...
;             PG8_LDA(At, 1, 1); PG8_STAGE(PG8_SB(1, 0), b3, voffB); PG8_STAGE(PG8_SB(1, 1), b3 + hstep, voffB); PG8_STAGE(PG8_SA(1, 0), a3, voffA);
;             PG8_WAIT_V(8); PG8_WAIT_L(0); PG8_BAR; PG8_MMA(1, 0, At, B0); PG8_MMA(1, 1, At, B1); PG8_BAR; PG8_SCHED;
	s_add_i32 s0, s0, s75
	v_lshl_add_u64 v[214:215], v[214:215], 0, s[40:41]
	s_mov_b32 m0, s0
	ds_read_b128 v[160:163], v226 offset:49152
	ds_read_b128 v[164:167], v226 offset:50176
	ds_read_b128 v[168:171], v226 offset:51200
	ds_read_b128 v[172:175], v226 offset:52224
	ds_read_b128 v[196:199], v226 offset:53248
	ds_read_b128 v[200:203], v226 offset:54272
	ds_read_b128 v[204:207], v226 offset:55296
	ds_read_b128 v[210:213], v226 offset:56320
	global_load_lds_dwordx4 v[214:215], off
	s_add_i32 m0, s0, 0x2000
	s_add_u32 s12, s12, 0x40080
	v_lshl_add_u64 v[214:215], v[216:217], 0, s[40:41]
	s_addc_u32 s13, s13, 0
	s_add_i32 s0, s1, s75
	global_load_lds_dwordx4 v[214:215], off
	v_lshl_add_u64 v[214:215], s[12:13], 0, v[178:179]
	s_mov_b32 m0, s0
	s_nop 0
	global_load_lds_dwordx4 v[214:215], off
	v_lshl_add_u64 v[214:215], s[12:13], 0, v[182:183]
	s_add_i32 m0, s0, 0x2000
	s_nop 0
	global_load_lds_dwordx4 v[214:215], off
	v_lshl_add_u64 v[214:215], v[218:219], 0, s[40:41]
	s_mov_b32 m0, s85
	s_nop 0
	global_load_lds_dwordx4 v[214:215], off
	v_lshl_add_u64 v[214:215], v[220:221], 0, s[40:41]
	s_mov_b32 m0, s86
	s_nop 0
	global_load_lds_dwordx4 v[214:215], off
	s_waitcnt vmcnt(8)
	s_waitcnt lgkmcnt(0)
	s_barrier
	s_setprio 1
	s_waitcnt lgkmcnt(0)
	v_mfma_f32_16x16x32_bf16 v[68:71], v[128:131], v[160:163], v[68:71]
	v_mfma_f32_16x16x32_bf16 v[20:23], v[136:139], v[160:163], v[20:23]
	v_mfma_f32_16x16x32_bf16 v[60:63], v[128:131], v[168:171], v[60:63]
	v_mfma_f32_16x16x32_bf16 v[12:15], v[136:139], v[168:171], v[12:15]
	v_mfma_f32_16x16x32_bf16 v[52:55], v[128:131], v[196:199], v[52:55]
	v_mfma_f32_16x16x32_bf16 v[4:7], v[136:139], v[196:199], v[4:7]
	v_mfma_f32_16x16x32_bf16 v[108:111], v[128:131], v[204:207], v[108:111]
	v_mfma_f32_16x16x32_bf16 v[104:107], v[136:139], v[204:207], v[104:107]
	v_mfma_f32_16x16x32_bf16 v[68:71], v[132:135], v[164:167], v[68:71]
	v_mfma_f32_16x16x32_bf16 v[20:23], v[140:143], v[164:167], v[20:23]
	v_mfma_f32_16x16x32_bf16 v[60:63], v[132:135], v[172:175], v[60:63]
	v_mfma_f32_16x16x32_bf16 v[12:15], v[140:143], v[172:175], v[12:15]
	v_mfma_f32_16x16x32_bf16 v[52:55], v[132:135], v[200:203], v[52:55]
	v_mfma_f32_16x16x32_bf16 v[4:7], v[140:143], v[200:203], v[4:7]
	v_mfma_f32_16x16x32_bf16 v[108:111], v[132:135], v[210:213], v[108:111]
	v_mfma_f32_16x16x32_bf16 v[104:107], v[140:143], v[210:213], v[104:107]
	s_setprio 0
	s_setprio 1
	v_mfma_f32_16x16x32_bf16 v[64:67], v[144:147], v[160:163], v[64:67]
	v_mfma_f32_16x16x32_bf16 v[16:19], v[152:155], v[160:163], v[16:19]
	v_mfma_f32_16x16x32_bf16 v[56:59], v[144:147], v[168:171], v[56:59]
	v_mfma_f32_16x16x32_bf16 v[8:11], v[152:155], v[168:171], v[8:11]
	v_mfma_f32_16x16x32_bf16 v[48:51], v[144:147], v[196:199], v[48:51]
	v_mfma_f32_16x16x32_bf16 v[0:3], v[152:155], v[196:199], v[0:3]
	v_mfma_f32_16x16x32_bf16 v[100:103], v[144:147], v[204:207], v[100:103]
	v_mfma_f32_16x16x32_bf16 v[96:99], v[152:155], v[204:207], v[96:99]
	v_mfma_f32_16x16x32_bf16 v[64:67], v[148:151], v[164:167], v[64:67]
	v_mfma_f32_16x16x32_bf16 v[16:19], v[156:159], v[164:167], v[16:19]
	v_mfma_f32_16x16x32_bf16 v[56:59], v[148:151], v[172:175], v[56:59]
	v_mfma_f32_16x16x32_bf16 v[8:11], v[156:159], v[172:175], v[8:11]
	v_mfma_f32_16x16x32_bf16 v[48:51], v[148:151], v[200:203], v[48:51]
	v_mfma_f32_16x16x32_bf16 v[0:3], v[156:159], v[200:203], v[0:3]
	v_mfma_f32_16x16x32_bf16 v[100:103], v[148:151], v[210:213], v[100:103]
	v_mfma_f32_16x16x32_bf16 v[96:99], v[156:159], v[210:213], v[96:99]
	s_setprio 0
	s_add_i32 s21, s21, 2
	s_add_u32 s10, s10, 0x100
	s_addc_u32 s11, s11, 0
	s_add_u32 s19, s19, 0x100
	s_addc_u32 s20, s20, 0
	s_cmp_gt_u32 s21, 13
	s_cbranch_scc0 .Lkrot3
	s_barrier
	s_and_b64 vcc, exec, s[42:43]
	s_cbranch_vccnz .LBB0_579
	s_cmp_lg_u32 s18, 64
	s_mov_b64 s[10:11], -1
	s_cbranch_scc1 .LBB0_580

;     __device__ __forceinline__ long a_off(int pm, size_t tstep) const { return (long)pm * (long)tstep; }
; template <class Epi, class Sched, bool ALIGN_EPI = false, bool SP2 = false>
; __device__ __forceinline__ void gemm_phase(PG8_LAS unsigned char* lds, const Gemm g, const Sched& S, const Epi& E) {
;     ...
;         const char* nA = has_next ? (const char*)g.A + S.a_off(nxt.pm, tstep) : cA; const char* nB = has_next ? (const char*)g.Bt + (size_t)nxt.pn * tstep : cB;
;         for (int t = 0; t < nt; t += 2) {
;             const bool last = (t == nt - 2);
;             const char* a1 = cA + (size_t)(t + 1) * kstep;
;             const char* a2 = last ? nA : cA + (size_t)(t + 2) * kstep; const char* b2 = last ? nB : cB + (size_t)(t + 2) * kstep;
;     ...
;         for (int a = 0; a < 2; ++a)
; #pragma unroll
;             for (int b = 0; b < 2; ++b)
; #pragma unroll
;                 for (int m = 0; m < 4; ++m)
; #pragma unroll
;                     for (int n = 0; n < 2; ++n) acc[a][b][m][n] = (f32x4){0.f, 0.f, 0.f, 0.f};
.LBB0_673:
	s_add_u32 s22, s22, 0xb0080
	s_addc_u32 s23, s23, 0
	s_add_u32 s50, s24, 0x100
	v_mov_b32_e32 v0, 0
	s_addc_u32 s51, s25, 0
	s_mov_b32 s52, -2
	v_mov_b32_e32 v1, v0
	v_mov_b32_e32 v2, v0
	v_mov_b32_e32 v3, v0
	v_mov_b32_e32 v4, v0
	v_mov_b32_e32 v5, v0
	v_mov_b32_e32 v6, v0
	v_mov_b32_e32 v7, v0
	v_mov_b32_e32 v12, v0
	v_mov_b32_e32 v13, v0
	v_mov_b32_e32 v14, v0
	v_mov_b32_e32 v15, v0
	v_mov_b32_e32 v20, v0
	v_mov_b32_e32 v21, v0
	v_mov_b32_e32 v22, v0
	v_mov_b32_e32 v23, v0
	v_mov_b32_e32 v28, v0
	v_mov_b32_e32 v29, v0
	v_mov_b32_e32 v30, v0
	v_mov_b32_e32 v31, v0
	v_mov_b32_e32 v36, v0
	v_mov_b32_e32 v37, v0
	v_mov_b32_e32 v38, v0
	v_mov_b32_e32 v39, v0
	v_mov_b32_e32 v44, v0
	v_mov_b32_e32 v45, v0
	v_mov_b32_e32 v46, v0
	v_mov_b32_e32 v47, v0
	v_mov_b32_e32 v52, v0
	v_mov_b32_e32 v53, v0
	v_mov_b32_e32 v54, v0
	v_mov_b32_e32 v55, v0
	v_mov_b32_e32 v8, v0
	v_mov_b32_e32 v9, v0
	v_mov_b32_e32 v10, v0
	v_mov_b32_e32 v11, v0
	v_mov_b32_e32 v16, v0
	v_mov_b32_e32 v17, v0
	v_mov_b32_e32 v18, v0
	v_mov_b32_e32 v19, v0
	v_mov_b32_e32 v24, v0
	v_mov_b32_e32 v25, v0
	v_mov_b32_e32 v26, v0
	v_mov_b32_e32 v27, v0
	v_mov_b32_e32 v32, v0
	v_mov_b32_e32 v33, v0
	v_mov_b32_e32 v34, v0
	v_mov_b32_e32 v35, v0
	v_mov_b32_e32 v40, v0
	v_mov_b32_e32 v41, v0
	v_mov_b32_e32 v42, v0
	v_mov_b32_e32 v43, v0
	v_mov_b32_e32 v48, v0
	v_mov_b32_e32 v49, v0
	v_mov_b32_e32 v50, v0
	v_mov_b32_e32 v51, v0
	v_mov_b32_e32 v56, v0
	v_mov_b32_e32 v57, v0
	v_mov_b32_e32 v58, v0
	v_mov_b32_e32 v59, v0
	v_mov_b32_e32 v60, v0
	v_mov_b32_e32 v61, v0
	v_mov_b32_e32 v62, v0
	v_mov_b32_e32 v63, v0
	v_mov_b32_e32 v64, v0
	v_mov_b32_e32 v65, v0
	v_mov_b32_e32 v66, v0
	v_mov_b32_e32 v67, v0
	v_mov_b32_e32 v68, v0
	v_mov_b32_e32 v69, v0
	v_mov_b32_e32 v70, v0
	v_mov_b32_e32 v71, v0
	v_mov_b32_e32 v76, v0
	v_mov_b32_e32 v77, v0
	v_mov_b32_e32 v78, v0
	v_mov_b32_e32 v79, v0
	v_mov_b32_e32 v84, v0
	v_mov_b32_e32 v85, v0
	v_mov_b32_e32 v86, v0
	v_mov_b32_e32 v87, v0
	v_mov_b32_e32 v92, v0
	v_mov_b32_e32 v93, v0
	v_mov_b32_e32 v94, v0
	v_mov_b32_e32 v95, v0
	v_mov_b32_e32 v100, v0
	v_mov_b32_e32 v101, v0
	v_mov_b32_e32 v102, v0
	v_mov_b32_e32 v103, v0
	v_mov_b32_e32 v104, v0
	v_mov_b32_e32 v105, v0
	v_mov_b32_e32 v106, v0
	v_mov_b32_e32 v107, v0
	v_mov_b32_e32 v108, v0
	v_mov_b32_e32 v109, v0
	v_mov_b32_e32 v110, v0
	v_mov_b32_e32 v111, v0
	v_mov_b32_e32 v72, v0
	v_mov_b32_e32 v73, v0
	v_mov_b32_e32 v74, v0
	v_mov_b32_e32 v75, v0
	v_mov_b32_e32 v80, v0
	v_mov_b32_e32 v81, v0
	v_mov_b32_e32 v82, v0
	v_mov_b32_e32 v83, v0
	v_mov_b32_e32 v88, v0
	v_mov_b32_e32 v89, v0
	v_mov_b32_e32 v90, v0
	v_mov_b32_e32 v91, v0
	v_mov_b32_e32 v96, v0
	v_mov_b32_e32 v97, v0
	v_mov_b32_e32 v98, v0
	v_mov_b32_e32 v99, v0
	v_mov_b32_e32 v112, v0
	v_mov_b32_e32 v113, v0
	v_mov_b32_e32 v114, v0
	v_mov_b32_e32 v115, v0
	v_mov_b32_e32 v116, v0
	v_mov_b32_e32 v117, v0
	v_mov_b32_e32 v118, v0
	v_mov_b32_e32 v119, v0
	v_mov_b32_e32 v120, v0
	v_mov_b32_e32 v121, v0
	v_mov_b32_e32 v122, v0
	v_mov_b32_e32 v123, v0
	v_mov_b32_e32 v124, v0
	v_mov_b32_e32 v125, v0
	v_mov_b32_e32 v126, v0
	v_mov_b32_e32 v127, v0
	s_branch .LBB0_674

; #define PG8_STAGE(bufoff, gbase, voff) do { _Pragma("unroll") for (int _i = 0; _i < 2; ++_i) \
;         __builtin_amdgcn_global_load_lds((const unsigned*)((const char*)(gbase) + (voff)[_i]), (PG8_LAS unsigned*)(lds + (bufoff) + ldsw + _i * 8192), 16, 0, 0); } while (0)
; #define PG8_LDA(dst, b, h) do { _Pragma("unroll") for (int m = 0; m < 4; ++m) _Pragma("unroll") for (int k = 0; k < 2; ++k) dst[m][k] = *(const PG8_LAS bf16x8*)(lds + PG8_SA(b, h) + aoff + m * 2048 + k * 1024); } while (0)
; #define PG8_LDB(dst, b, h) do { _Pragma("unroll") for (int n = 0; n < 2; ++n) _Pragma("unroll") for (int k = 0; k < 2; ++k) dst[n][k] = *(const PG8_LAS bf16x8*)(lds + PG8_SB(b, h) + boff + n * 2048 + k * 1024); } while (0)
; #define PG8_MMA(ai, bj, At, Bt) do { __builtin_amdgcn_s_setprio(1); _Pragma("unroll") for (int m = 0; m < 4; ++m) _Pragma("unroll") for (int n = 0; n < 2; ++n) _Pragma("unroll") for (int k = 0; k < 2; ++k) \
;         acc[ai][bj][m][n] = __builtin_amdgcn_mfma_f32_16x16x32_bf16(Bt[n][k], At[m][k], acc[ai][bj][m][n], 0, 0, 0); __builtin_amdgcn_s_setprio(0); } while (0)
; #define PG8_WAIT_V(n) asm volatile("s_waitcnt vmcnt(" #n ")" ::: "memory")
; #define PG8_WAIT_L(n) asm volatile("s_waitcnt lgkmcnt(" #n ")" ::: "memory")
; #define PG8_BAR __builtin_amdgcn_s_barrier()
; #define PG8_SCHED __builtin_amdgcn_sched_barrier(0)
; template <class Epi, class Sched, bool ALIGN_EPI = false, bool SP2 = false>
; __device__ __forceinline__ void gemm_phase(PG8_LAS unsigned char* lds, const Gemm g, const Sched& S, const Epi& E) {
;     ...
;             PG8_LDB(B0, 0, 0); PG8_LDB(B1, 0, 1); PG8_SCHED; PG8_LDA(At, 0, 0); PG8_STAGE(PG8_SA(1, 1), a1 + hstep, voffA);
;             PG8_WAIT_V(8); PG8_WAIT_L(0); PG8_BAR; PG8_MMA(0, 0, At, B0); PG8_MMA(0, 1, At, B1); PG8_BAR; PG8_SCHED;
;             PG8_LDA(At, 0, 1); PG8_STAGE(PG8_SB(0, 0), b2, voffB); PG8_STAGE(PG8_SB(0, 1), b2 + hstep, voffB); PG8_STAGE(PG8_SA(0, 0), a2, voffA);
;             PG8_WAIT_V(8); PG8_WAIT_L(0); PG8_BAR; PG8_MMA(1, 0, At, B0); PG8_MMA(1, 1, At, B1); PG8_BAR; PG8_SCHED;
.LBB0_674:
	ds_read_b128 v[128:131], v171
	ds_read_b128 v[132:135], v171 offset:1024
	ds_read_b128 v[136:139], v171 offset:2048
	ds_read_b128 v[140:143], v171 offset:3072
	ds_read_b128 v[162:165], v172
	ds_read_b128 v[174:177], v172 offset:1024
	ds_read_b128 v[178:181], v172 offset:2048
	ds_read_b128 v[182:185], v172 offset:3072
	s_add_u32 s24, s22, 0xfff50080
	s_addc_u32 s25, s23, -1
	s_cmp_eq_u32 s52, 40
	s_cselect_b32 s29, s5, s25
	s_cselect_b32 s28, s4, s24
	s_cselect_b32 s25, s21, s51
	s_cselect_b32 s24, s20, s50
	v_lshl_add_u64 v[166:167], s[22:23], 0, v[154:155]
	s_add_i32 m0, s35, 0xc000
	ds_read_b128 v[186:189], v173
	ds_read_b128 v[190:193], v173 offset:1024
	ds_read_b128 v[194:197], v173 offset:2048
	ds_read_b128 v[198:201], v173 offset:3072
	ds_read_b128 v[202:205], v173 offset:4096
	ds_read_b128 v[206:209], v173 offset:5120
	ds_read_b128 v[210:213], v173 offset:6144
	ds_read_b128 v[214:217], v173 offset:7168
	global_load_lds_dwordx4 v[166:167], off
	v_lshl_add_u64 v[166:167], s[22:23], 0, v[156:157]
	s_add_i32 m0, s35, 0xe000
	s_nop 0
	global_load_lds_dwordx4 v[166:167], off
	s_waitcnt vmcnt(8)
	s_waitcnt lgkmcnt(0)
	s_barrier
	s_setprio 1
	s_waitcnt lgkmcnt(0)
	v_mfma_f32_16x16x32_bf16 v[124:127], v[128:131], v[186:189], v[124:127]
	v_mfma_f32_16x16x32_bf16 v[120:123], v[136:139], v[186:189], v[120:123]
	v_mfma_f32_16x16x32_bf16 v[116:119], v[128:131], v[194:197], v[116:119]
	v_mfma_f32_16x16x32_bf16 v[112:115], v[136:139], v[194:197], v[112:115]
	v_mfma_f32_16x16x32_bf16 v[96:99], v[128:131], v[202:205], v[96:99]
	v_mfma_f32_16x16x32_bf16 v[88:91], v[136:139], v[202:205], v[88:91]
	v_mfma_f32_16x16x32_bf16 v[80:83], v[128:131], v[210:213], v[80:83]
	v_mfma_f32_16x16x32_bf16 v[72:75], v[136:139], v[210:213], v[72:75]
	v_mfma_f32_16x16x32_bf16 v[124:127], v[132:135], v[190:193], v[124:127]
	v_mfma_f32_16x16x32_bf16 v[120:123], v[140:143], v[190:193], v[120:123]
	v_mfma_f32_16x16x32_bf16 v[116:119], v[132:135], v[198:201], v[116:119]
	v_mfma_f32_16x16x32_bf16 v[112:115], v[140:143], v[198:201], v[112:115]
	v_mfma_f32_16x16x32_bf16 v[96:99], v[132:135], v[206:209], v[96:99]
	v_mfma_f32_16x16x32_bf16 v[88:91], v[140:143], v[206:209], v[88:91]
	v_mfma_f32_16x16x32_bf16 v[80:83], v[132:135], v[214:217], v[80:83]
	v_mfma_f32_16x16x32_bf16 v[72:75], v[140:143], v[214:217], v[72:75]
	s_setprio 0
	s_setprio 1
	v_mfma_f32_16x16x32_bf16 v[108:111], v[162:165], v[186:189], v[108:111]
	v_mfma_f32_16x16x32_bf16 v[104:107], v[178:181], v[186:189], v[104:107]
	v_mfma_f32_16x16x32_bf16 v[100:103], v[162:165], v[194:197], v[100:103]
	v_mfma_f32_16x16x32_bf16 v[92:95], v[178:181], v[194:197], v[92:95]
	v_mfma_f32_16x16x32_bf16 v[84:87], v[162:165], v[202:205], v[84:87]
	v_mfma_f32_16x16x32_bf16 v[76:79], v[178:181], v[202:205], v[76:79]
	v_mfma_f32_16x16x32_bf16 v[68:71], v[162:165], v[210:213], v[68:71]
	v_mfma_f32_16x16x32_bf16 v[64:67], v[178:181], v[210:213], v[64:67]
	v_mfma_f32_16x16x32_bf16 v[108:111], v[174:177], v[190:193], v[108:111]
	v_mfma_f32_16x16x32_bf16 v[104:107], v[182:185], v[190:193], v[104:107]
	v_mfma_f32_16x16x32_bf16 v[100:103], v[174:177], v[198:201], v[100:103]
	v_mfma_f32_16x16x32_bf16 v[92:95], v[182:185], v[198:201], v[92:95]
	v_mfma_f32_16x16x32_bf16 v[84:87], v[174:177], v[206:209], v[84:87]
	v_mfma_f32_16x16x32_bf16 v[76:79], v[182:185], v[206:209], v[76:79]
	v_mfma_f32_16x16x32_bf16 v[68:71], v[174:177], v[214:217], v[68:71]
	v_mfma_f32_16x16x32_bf16 v[64:67], v[182:185], v[214:217], v[64:67]
	s_setprio 0
	s_barrier
	s_add_i32 s53, s43, s34
	v_lshl_add_u64 v[166:167], s[24:25], 0, v[146:147]
	s_mov_b32 m0, s53
	ds_read_b128 v[186:189], v173 offset:16384
	ds_read_b128 v[190:193], v173 offset:17408
	ds_read_b128 v[194:197], v173 offset:18432
	ds_read_b128 v[198:201], v173 offset:19456
	ds_read_b128 v[202:205], v173 offset:20480
	ds_read_b128 v[206:209], v173 offset:21504
	ds_read_b128 v[210:213], v173 offset:22528
	ds_read_b128 v[214:217], v173 offset:23552
	global_load_lds_dwordx4 v[166:167], off
	s_add_i32 m0, s53, 0x2000
	s_add_u32 s54, s24, 0xb0000
	v_lshl_add_u64 v[218:219], s[24:25], 0, v[150:151]
	s_addc_u32 s55, s25, 0
	s_add_i32 s53, s44, s34
	global_load_lds_dwordx4 v[218:219], off
	v_lshl_add_u64 v[220:221], s[54:55], 0, v[146:147]
	s_mov_b32 m0, s53
	v_lshl_add_u64 v[222:223], s[28:29], 0, v[148:149]
	global_load_lds_dwordx4 v[220:221], off
	v_lshl_add_u64 v[220:221], s[54:55], 0, v[150:151]
	s_add_i32 m0, s53, 0x2000
	s_nop 0
	global_load_lds_dwordx4 v[220:221], off
	v_lshl_add_u64 v[220:221], s[28:29], 0, v[144:145]
	s_mov_b32 m0, s35
	s_nop 0
	global_load_lds_dwordx4 v[220:221], off
	s_mov_b32 m0, s36
	s_nop 0
	global_load_lds_dwordx4 v[222:223], off
	s_waitcnt vmcnt(8)
	s_waitcnt lgkmcnt(0)
	s_barrier
; #define PG8_STAGE(bufoff, gbase, voff) do { _Pragma("unroll") for (int _i = 0; _i < 2; ++_i) \
;         __builtin_amdgcn_global_load_lds((const unsigned*)((const char*)(gbase) + (voff)[_i]), (PG8_LAS unsigned*)(lds + (bufoff) + ldsw + _i * 8192), 16, 0, 0); } while (0)
; #define PG8_LDA(dst, b, h) do { _Pragma("unroll") for (int m = 0; m < 4; ++m) _Pragma("unroll") for (int k = 0; k < 2; ++k) dst[m][k] = *(const PG8_LAS bf16x8*)(lds + PG8_SA(b, h) + aoff + m * 2048 + k * 1024); } while (0)
; #define PG8_LDB(dst, b, h) do { _Pragma("unroll") for (int n = 0; n < 2; ++n) _Pragma("unroll") for (int k = 0; k < 2; ++k) dst[n][k] = *(const PG8_LAS bf16x8*)(lds + PG8_SB(b, h) + boff + n * 2048 + k * 1024); } while (0)
; #define PG8_MMA(ai, bj, At, Bt) do { __builtin_amdgcn_s_setprio(1); _Pragma("unroll") for (int m = 0; m < 4; ++m) _Pragma("unroll") for (int n = 0; n < 2; ++n) _Pragma("unroll") for (int k = 0; k < 2; ++k) \
;         acc[ai][bj][m][n] = __builtin_amdgcn_mfma_f32_16x16x32_bf16(Bt[n][k], At[m][k], acc[ai][bj][m][n], 0, 0, 0); __builtin_amdgcn_s_setprio(0); } while (0)
; #define PG8_WAIT_V(n) asm volatile("s_waitcnt vmcnt(" #n ")" ::: "memory")
; #define PG8_WAIT_L(n) asm volatile("s_waitcnt lgkmcnt(" #n ")" ::: "memory")
; #define PG8_BAR __builtin_amdgcn_s_barrier()
; #define PG8_SCHED __builtin_amdgcn_sched_barrier(0)
; template <class Epi, class Sched, bool ALIGN_EPI = false, bool SP2 = false>
; __device__ __forceinline__ void gemm_phase(PG8_LAS unsigned char* lds, const Gemm g, const Sched& S, const Epi& E) {
;     ...
;             PG8_WAIT_V(8); PG8_WAIT_L(0); PG8_BAR; PG8_MMA(1, 0, At, B0); PG8_MMA(1, 1, At, B1); PG8_BAR; PG8_SCHED;
;             PG8_LDB(B0, 1, 0); PG8_LDB(B1, 1, 1); PG8_SCHED; PG8_LDA(At, 1, 0); PG8_STAGE(PG8_SA(0, 1), a2 + hstep, voffA);
;             PG8_WAIT_V(8); PG8_WAIT_L(0); PG8_BAR; PG8_MMA(0, 0, At, B0); PG8_MMA(0, 1, At, B1); PG8_BAR; PG8_SCHED;
	s_setprio 1
	s_waitcnt lgkmcnt(0)
	v_mfma_f32_16x16x32_bf16 v[60:63], v[128:131], v[186:189], v[60:63]
	v_mfma_f32_16x16x32_bf16 v[56:59], v[136:139], v[186:189], v[56:59]
	v_mfma_f32_16x16x32_bf16 v[48:51], v[128:131], v[194:197], v[48:51]
	v_mfma_f32_16x16x32_bf16 v[40:43], v[136:139], v[194:197], v[40:43]
	v_mfma_f32_16x16x32_bf16 v[32:35], v[128:131], v[202:205], v[32:35]
	v_mfma_f32_16x16x32_bf16 v[24:27], v[136:139], v[202:205], v[24:27]
	v_mfma_f32_16x16x32_bf16 v[16:19], v[128:131], v[210:213], v[16:19]
	v_mfma_f32_16x16x32_bf16 v[8:11], v[136:139], v[210:213], v[8:11]
	v_mfma_f32_16x16x32_bf16 v[60:63], v[132:135], v[190:193], v[60:63]
	v_mfma_f32_16x16x32_bf16 v[56:59], v[140:143], v[190:193], v[56:59]
	v_mfma_f32_16x16x32_bf16 v[48:51], v[132:135], v[198:201], v[48:51]
	v_mfma_f32_16x16x32_bf16 v[40:43], v[140:143], v[198:201], v[40:43]
	v_mfma_f32_16x16x32_bf16 v[32:35], v[132:135], v[206:209], v[32:35]
	v_mfma_f32_16x16x32_bf16 v[24:27], v[140:143], v[206:209], v[24:27]
	v_mfma_f32_16x16x32_bf16 v[16:19], v[132:135], v[214:217], v[16:19]
	v_mfma_f32_16x16x32_bf16 v[8:11], v[140:143], v[214:217], v[8:11]
	s_setprio 0
	s_setprio 1
	v_mfma_f32_16x16x32_bf16 v[52:55], v[162:165], v[186:189], v[52:55]
	v_mfma_f32_16x16x32_bf16 v[44:47], v[178:181], v[186:189], v[44:47]
	v_mfma_f32_16x16x32_bf16 v[36:39], v[162:165], v[194:197], v[36:39]
	v_mfma_f32_16x16x32_bf16 v[28:31], v[178:181], v[194:197], v[28:31]
	v_mfma_f32_16x16x32_bf16 v[20:23], v[162:165], v[202:205], v[20:23]
	v_mfma_f32_16x16x32_bf16 v[12:15], v[178:181], v[202:205], v[12:15]
	v_mfma_f32_16x16x32_bf16 v[4:7], v[162:165], v[210:213], v[4:7]
	v_mfma_f32_16x16x32_bf16 v[0:3], v[178:181], v[210:213], v[0:3]
	v_mfma_f32_16x16x32_bf16 v[52:55], v[174:177], v[190:193], v[52:55]
	v_mfma_f32_16x16x32_bf16 v[44:47], v[182:185], v[190:193], v[44:47]
	v_mfma_f32_16x16x32_bf16 v[36:39], v[174:177], v[198:201], v[36:39]
	v_mfma_f32_16x16x32_bf16 v[28:31], v[182:185], v[198:201], v[28:31]
	v_mfma_f32_16x16x32_bf16 v[20:23], v[174:177], v[206:209], v[20:23]
	v_mfma_f32_16x16x32_bf16 v[12:15], v[182:185], v[206:209], v[12:15]
	v_mfma_f32_16x16x32_bf16 v[4:7], v[174:177], v[214:217], v[4:7]
	v_mfma_f32_16x16x32_bf16 v[0:3], v[182:185], v[214:217], v[0:3]
	s_setprio 0
	s_barrier
	s_add_i32 s53, 0, 0x18000
	s_add_i32 s54, 0, 0x1c000
	v_add_u32_e32 v140, s53, v168
	v_add_u32_e32 v152, s54, v168
	ds_read_b128 v[128:131], v140
	ds_read_b128 v[132:135], v140 offset:1024
	ds_read_b128 v[136:139], v140 offset:2048
	ds_read_b128 v[140:143], v140 offset:3072
	ds_read_b128 v[162:165], v152
	ds_read_b128 v[174:177], v152 offset:1024
	ds_read_b128 v[178:181], v152 offset:2048
	ds_read_b128 v[182:185], v152 offset:3072
	s_add_u32 s28, s28, 0xb0000
	s_addc_u32 s29, s29, 0
	s_mov_b32 m0, s37
	v_lshl_add_u64 v[224:225], s[28:29], 0, v[144:145]
	ds_read_b128 v[186:189], v173 offset:32768
	ds_read_b128 v[190:193], v173 offset:33792
	ds_read_b128 v[194:197], v173 offset:34816
	ds_read_b128 v[198:201], v173 offset:35840
	ds_read_b128 v[202:205], v173 offset:36864
	ds_read_b128 v[206:209], v173 offset:37888
	ds_read_b128 v[210:213], v173 offset:38912
	ds_read_b128 v[214:217], v173 offset:39936
	global_load_lds_dwordx4 v[224:225], off
	v_lshl_add_u64 v[224:225], s[28:29], 0, v[148:149]
	s_mov_b32 m0, s38
	s_nop 0
	global_load_lds_dwordx4 v[224:225], off
	s_waitcnt vmcnt(8)
	s_waitcnt lgkmcnt(0)
	s_barrier
	s_setprio 1
	s_waitcnt lgkmcnt(0)
	v_mfma_f32_16x16x32_bf16 v[124:127], v[128:131], v[186:189], v[124:127]
	v_mfma_f32_16x16x32_bf16 v[120:123], v[136:139], v[186:189], v[120:123]
	v_mfma_f32_16x16x32_bf16 v[116:119], v[128:131], v[194:197], v[116:119]
	v_mfma_f32_16x16x32_bf16 v[112:115], v[136:139], v[194:197], v[112:115]
	v_mfma_f32_16x16x32_bf16 v[96:99], v[128:131], v[202:205], v[96:99]
	v_mfma_f32_16x16x32_bf16 v[88:91], v[136:139], v[202:205], v[88:91]
	v_mfma_f32_16x16x32_bf16 v[80:83], v[128:131], v[210:213], v[80:83]
	v_mfma_f32_16x16x32_bf16 v[72:75], v[136:139], v[210:213], v[72:75]
	v_mfma_f32_16x16x32_bf16 v[124:127], v[132:135], v[190:193], v[124:127]
	v_mfma_f32_16x16x32_bf16 v[120:123], v[140:143], v[190:193], v[120:123]
	v_mfma_f32_16x16x32_bf16 v[116:119], v[132:135], v[198:201], v[116:119]
	v_mfma_f32_16x16x32_bf16 v[112:115], v[140:143], v[198:201], v[112:115]
	v_mfma_f32_16x16x32_bf16 v[96:99], v[132:135], v[206:209], v[96:99]
	v_mfma_f32_16x16x32_bf16 v[88:91], v[140:143], v[206:209], v[88:91]
	v_mfma_f32_16x16x32_bf16 v[80:83], v[132:135], v[214:217], v[80:83]
	v_mfma_f32_16x16x32_bf16 v[72:75], v[140:143], v[214:217], v[72:75]
	s_setprio 0
	s_setprio 1
	v_mfma_f32_16x16x32_bf16 v[108:111], v[162:165], v[186:189], v[108:111]
	v_mfma_f32_16x16x32_bf16 v[104:107], v[178:181], v[186:189], v[104:107]
	v_mfma_f32_16x16x32_bf16 v[100:103], v[162:165], v[194:197], v[100:103]
	v_mfma_f32_16x16x32_bf16 v[92:95], v[178:181], v[194:197], v[92:95]
	v_mfma_f32_16x16x32_bf16 v[84:87], v[162:165], v[202:205], v[84:87]
	v_mfma_f32_16x16x32_bf16 v[76:79], v[178:181], v[202:205], v[76:79]
	v_mfma_f32_16x16x32_bf16 v[68:71], v[162:165], v[210:213], v[68:71]
	v_mfma_f32_16x16x32_bf16 v[64:67], v[178:181], v[210:213], v[64:67]
	v_mfma_f32_16x16x32_bf16 v[108:111], v[174:177], v[190:193], v[108:111]
	v_mfma_f32_16x16x32_bf16 v[104:107], v[182:185], v[190:193], v[104:107]
	v_mfma_f32_16x16x32_bf16 v[100:103], v[174:177], v[198:201], v[100:103]
	v_mfma_f32_16x16x32_bf16 v[92:95], v[182:185], v[198:201], v[92:95]
	v_mfma_f32_16x16x32_bf16 v[84:87], v[174:177], v[206:209], v[84:87]
	v_mfma_f32_16x16x32_bf16 v[76:79], v[182:185], v[206:209], v[76:79]
	v_mfma_f32_16x16x32_bf16 v[68:71], v[174:177], v[214:217], v[68:71]
	v_mfma_f32_16x16x32_bf16 v[64:67], v[182:185], v[214:217], v[64:67]
	s_setprio 0
	s_barrier
; #define PG8_STAGE(bufoff, gbase, voff) do { _Pragma("unroll") for (int _i = 0; _i < 2; ++_i) \
;         __builtin_amdgcn_global_load_lds((const unsigned*)((const char*)(gbase) + (voff)[_i]), (PG8_LAS unsigned*)(lds + (bufoff) + ldsw + _i * 8192), 16, 0, 0); } while (0)
; #define PG8_LDA(dst, b, h) do { _Pragma("unroll") for (int m = 0; m < 4; ++m) _Pragma("unroll") for (int k = 0; k < 2; ++k) dst[m][k] = *(const PG8_LAS bf16x8*)(lds + PG8_SA(b, h) + aoff + m * 2048 + k * 1024); } while (0)
; #define PG8_MMA(ai, bj, At, Bt) do { __builtin_amdgcn_s_setprio(1); _Pragma("unroll") for (int m = 0; m < 4; ++m) _Pragma("unroll") for (int n = 0; n < 2; ++n) _Pragma("unroll") for (int k = 0; k < 2; ++k) \
;         acc[ai][bj][m][n] = __builtin_amdgcn_mfma_f32_16x16x32_bf16(Bt[n][k], At[m][k], acc[ai][bj][m][n], 0, 0, 0); __builtin_amdgcn_s_setprio(0); } while (0)
; #define PG8_WAIT_V(n) asm volatile("s_waitcnt vmcnt(" #n ")" ::: "memory")
; #define PG8_WAIT_L(n) asm volatile("s_waitcnt lgkmcnt(" #n ")" ::: "memory")
; #define PG8_BAR __builtin_amdgcn_s_barrier()
; #define PG8_SCHED __builtin_amdgcn_sched_barrier(0)
; template <class Epi, class Sched, bool ALIGN_EPI = false, bool SP2 = false>
; __device__ __forceinline__ void gemm_phase(PG8_LAS unsigned char* lds, const Gemm g, const Sched& S, const Epi& E) {
;     ...
;         for (int t = 0; t < nt; t += 2) {
;     ...
;             PG8_LDA(At, 1, 1); PG8_STAGE(PG8_SB(1, 0), b3, voffB); PG8_STAGE(PG8_SB(1, 1), b3 + hstep, voffB); PG8_STAGE(PG8_SA(1, 0), a3, voffA);
;             PG8_WAIT_V(8); PG8_WAIT_L(0); PG8_BAR; PG8_MMA(1, 0, At, B0); PG8_MMA(1, 1, At, B1); PG8_BAR; PG8_SCHED;
	s_add_i32 s28, s53, s34
	v_lshl_add_u64 v[166:167], v[166:167], 0, s[14:15]
	s_mov_b32 m0, s28
	ds_read_b128 v[186:189], v173 offset:49152
	ds_read_b128 v[190:193], v173 offset:50176
	ds_read_b128 v[194:197], v173 offset:51200
	ds_read_b128 v[198:201], v173 offset:52224
	ds_read_b128 v[202:205], v173 offset:53248
	ds_read_b128 v[206:209], v173 offset:54272
	ds_read_b128 v[210:213], v173 offset:55296
	ds_read_b128 v[214:217], v173 offset:56320
	global_load_lds_dwordx4 v[166:167], off
	s_add_i32 m0, s28, 0x2000
	s_add_u32 s24, s24, 0xb0080
	v_lshl_add_u64 v[166:167], v[218:219], 0, s[14:15]
	s_addc_u32 s25, s25, 0
	s_add_i32 s28, s54, s34
	global_load_lds_dwordx4 v[166:167], off
	v_lshl_add_u64 v[166:167], s[24:25], 0, v[146:147]
	s_mov_b32 m0, s28
	s_nop 0
	global_load_lds_dwordx4 v[166:167], off
	v_lshl_add_u64 v[166:167], s[24:25], 0, v[150:151]
	s_add_i32 m0, s28, 0x2000
	s_nop 0
	global_load_lds_dwordx4 v[166:167], off
	v_lshl_add_u64 v[166:167], v[220:221], 0, s[14:15]
	s_mov_b32 m0, s40
	s_nop 0
	global_load_lds_dwordx4 v[166:167], off
	v_lshl_add_u64 v[166:167], v[222:223], 0, s[14:15]
	s_mov_b32 m0, s41
	s_nop 0
	global_load_lds_dwordx4 v[166:167], off
	s_waitcnt vmcnt(8)
	s_waitcnt lgkmcnt(0)
	s_barrier
	s_setprio 1
	s_waitcnt lgkmcnt(0)
	v_mfma_f32_16x16x32_bf16 v[60:63], v[128:131], v[186:189], v[60:63]
	v_mfma_f32_16x16x32_bf16 v[56:59], v[136:139], v[186:189], v[56:59]
	v_mfma_f32_16x16x32_bf16 v[48:51], v[128:131], v[194:197], v[48:51]
	v_mfma_f32_16x16x32_bf16 v[40:43], v[136:139], v[194:197], v[40:43]
	v_mfma_f32_16x16x32_bf16 v[32:35], v[128:131], v[202:205], v[32:35]
	v_mfma_f32_16x16x32_bf16 v[24:27], v[136:139], v[202:205], v[24:27]
	v_mfma_f32_16x16x32_bf16 v[16:19], v[128:131], v[210:213], v[16:19]
	v_mfma_f32_16x16x32_bf16 v[8:11], v[136:139], v[210:213], v[8:11]
	v_mfma_f32_16x16x32_bf16 v[60:63], v[132:135], v[190:193], v[60:63]
	v_mfma_f32_16x16x32_bf16 v[56:59], v[140:143], v[190:193], v[56:59]
	v_mfma_f32_16x16x32_bf16 v[48:51], v[132:135], v[198:201], v[48:51]
	v_mfma_f32_16x16x32_bf16 v[40:43], v[140:143], v[198:201], v[40:43]
	v_mfma_f32_16x16x32_bf16 v[32:35], v[132:135], v[206:209], v[32:35]
	v_mfma_f32_16x16x32_bf16 v[24:27], v[140:143], v[206:209], v[24:27]
	v_mfma_f32_16x16x32_bf16 v[16:19], v[132:135], v[214:217], v[16:19]
	v_mfma_f32_16x16x32_bf16 v[8:11], v[140:143], v[214:217], v[8:11]
	s_setprio 0
	s_setprio 1
	v_mfma_f32_16x16x32_bf16 v[52:55], v[162:165], v[186:189], v[52:55]
	v_mfma_f32_16x16x32_bf16 v[44:47], v[178:181], v[186:189], v[44:47]
	v_mfma_f32_16x16x32_bf16 v[36:39], v[162:165], v[194:197], v[36:39]
	v_mfma_f32_16x16x32_bf16 v[28:31], v[178:181], v[194:197], v[28:31]
	v_mfma_f32_16x16x32_bf16 v[20:23], v[162:165], v[202:205], v[20:23]
	v_mfma_f32_16x16x32_bf16 v[12:15], v[178:181], v[202:205], v[12:15]
	v_mfma_f32_16x16x32_bf16 v[4:7], v[162:165], v[210:213], v[4:7]
	v_mfma_f32_16x16x32_bf16 v[0:3], v[178:181], v[210:213], v[0:3]
	v_mfma_f32_16x16x32_bf16 v[52:55], v[174:177], v[190:193], v[52:55]
	v_mfma_f32_16x16x32_bf16 v[44:47], v[182:185], v[190:193], v[44:47]
	v_mfma_f32_16x16x32_bf16 v[36:39], v[174:177], v[198:201], v[36:39]
	v_mfma_f32_16x16x32_bf16 v[28:31], v[182:185], v[198:201], v[28:31]
	v_mfma_f32_16x16x32_bf16 v[20:23], v[174:177], v[206:209], v[20:23]
	v_mfma_f32_16x16x32_bf16 v[12:15], v[182:185], v[206:209], v[12:15]
	v_mfma_f32_16x16x32_bf16 v[4:7], v[174:177], v[214:217], v[4:7]
	v_mfma_f32_16x16x32_bf16 v[0:3], v[182:185], v[214:217], v[0:3]
	s_setprio 0
	s_add_i32 s52, s52, 2
	s_add_u32 s22, s22, 0x100
	s_addc_u32 s23, s23, 0
	s_add_u32 s50, s50, 0x100
	s_addc_u32 s51, s51, 0
	s_cmp_gt_u32 s52, 41
	s_cbranch_scc0 .Lkrot4
	s_barrier
	s_and_b64 vcc, exec, s[16:17]
	s_cbranch_vccz .LBB0_677
	s_barrier
